# v17: RWKV scans: row-major bf16 LDS stores paired across lane neighbours (DPP + v_perm) into ds_write_b32 (80 pairs per chunk loop)
# speedup vs baseline: 1.0084x; 1.0084x over previous
; template <bool PA> ...
;     ...
;         for (int p = p0; p < p1; ++p) {
;             const int cidx = d ? nch - 1 - p : p; const int cbase = seqbase + cidx * 64;
;             float rv[8], kk[8], av[8], kd[8], lw[8]; u32x4_t tld = (u32x4_t){0u, 0u, 0u, 0u}, vraw = (u32x4_t){0u, 0u, 0u, 0u};
;             {
;                 const size_t row = cbase + (d ? 63 - j : j);
;                 asm volatile("" ::: "memory");
;                 if (haveT && tlow) tld = *(const u32x4_t*)(tbuf + ((size_t)strm * NCHA + p) * 2304 + tunit * 8);
;                 *(u32x4_t*)(MAT(4) + j * 72 + c8) = *(const u32x4_t*)(HWb + row * 128 + d * 64 + c8);
;                 *(u32x4_t*)(MAT(5) + j * 72 + c8) = *(const u32x4_t*)(HAb + row * 128 + d * 64 + c8);
;                 const u32x4_t rw = *(const u32x4_t*)(Rb + row * 1024 + hc8), kw = *(const u32x4_t*)(Kb + row * 1024 + hc8), vw = *(const u32x4_t*)(Vb + row * 1024 + hc8);
;     ...
;                 const float inv = rsqrtf(fmaxf(ss, 1e-24f));
; #pragma unroll
;                 for (int e = 0; e < 8; ++e) { av[e] = sigmoidf_(aa[e]); lw[e] = -0.6065306597f * sigmoidf_(z[e]); kd[e] = kv[e] * (1.0f + (av[e] - 1.0f) * cst[192 + c8 + e]); kk[e] *= inv; bsum += rv[e] * kd[e] * cst[256 + c8 + e]; }
;                 bsum += __shfl_xor(bsum, 1); bsum += __shfl_xor(bsum, 2); bsum += __shfl_xor(bsum, 4);
;                 if (!PA && part == 0) beta[((size_t)d * SLAB + row) * 16 + head] = bsum;
;                 *(f32x4_t*)(cumb + j * 64 + c8) = (f32x4_t){lw[0], lw[1], lw[2], lw[3]}; *(f32x4_t*)(cumb + j * 64 + c8 + 4) = (f32x4_t){lw[4], lw[5], lw[6], lw[7]};
;             }
;             __syncthreads();
;             { const int c = tid & 63, sg = tid >> 6; float run = 0.f;
; #pragma unroll
;               for (int i = 0; i < 8; ++i) { run += cumb[(8 * sg + i) * 64 + c]; cumb[(8 * sg + i) * 64 + c] = run; }
;               segtot[sg * 64 + c] = run; }
;             __syncthreads();
;             { const int c = tid & 63, sg = tid >> 6; float off = 0.f;
; #pragma unroll
;               for (int s = 0; s < 7; ++s) off += (s < sg) ? segtot[s * 64 + c] : 0.f;
; #pragma unroll
;               for (int i = 0; i < 8; ++i) cumb[(8 * sg + i) * 64 + c] += off; }
;             __syncthreads();
;             {
;                 const f32x4_t c0 = *(const f32x4_t*)(cumb + j * 64 + c8), c1 = *(const f32x4_t*)(cumb + j * 64 + c8 + 4);
.LBB0_150:
	s_lshl_b32 s13, s0, 5
	s_or_b32 s1, s13, 1
	s_cmp_lg_u32 s0, 0
	s_cselect_b32 s12, s1, 0
	s_add_i32 s13, s13, 33
	s_cmp_ge_i32 s12, s13
	s_cbranch_scc1 .LBB0_128
	s_lshr_b32 s0, s24, 5
	s_cmp_eq_u32 s9, 0
	s_cselect_b64 vcc, -1, 0
	s_mul_i32 s18, s0, 0x2040
	v_or_b32_e32 v0, s15, v85
	s_and_b64 s[0:1], vcc, exec
	v_readlane_b32 s20, v255, 30
	s_mov_b32 s0, 0x7980000
	v_lshlrev_b32_e32 v0, 1, v0
	v_readlane_b32 s21, v255, 31
	s_cselect_b32 s0, 0x5900000, s0
	v_cndmask_b32_e32 v10, v90, v84, vcc
	v_lshl_add_u64 v[70:71], s[20:21], 0, v[0:1]
	v_readlane_b32 s20, v255, 34
	s_add_u32 s0, s6, s0
	v_readlane_b32 s21, v255, 35
	s_addc_u32 s1, s7, 0
	v_add_u32_e32 v130, s18, v10
	s_mul_hi_i32 s15, s24, s91
	s_mul_i32 s18, s24, s91
	s_lshl_b32 s24, s9, 7
	v_lshl_add_u64 v[72:73], s[20:21], 0, v[0:1]
	v_readlane_b32 s20, v255, 28
	v_lshl_add_u64 v[66:67], v[42:43], 0, s[24:25]
	v_lshl_add_u64 v[68:69], v[44:45], 0, s[24:25]
	v_readlane_b32 s21, v255, 29
	s_mul_i32 s24, s9, 0x4100
	s_lshl_b32 s9, s11, 2
	v_readlane_b32 s11, v255, 14
	v_lshl_add_u64 v[74:75], s[20:21], 0, v[0:1]
	s_add_u32 s20, s11, s9
	v_readlane_b32 s9, v255, 15
	s_addc_u32 s21, s9, 0
	v_lshl_add_u64 v[76:77], s[0:1], 0, v[0:1]
	s_ashr_i32 s0, s12, 31
	s_add_u32 s1, s18, s12
	s_addc_u32 s0, s15, s0
	s_mul_i32 s9, s0, 0x1200
	v_mad_u64_u32 v[78:79], s[0:1], s1, v199, v[64:65]
	v_readlane_b32 s0, v255, 16
	v_add_u32_e32 v79, s9, v79
	s_sub_i32 s18, s0, s12
	v_mov_b32_e32 v228, 0
	v_mov_b32_e32 v229, 0
	v_mov_b32_e32 v230, 0
	v_mov_b32_e32 v231, 0
	s_and_saveexec_b64 s[0:1], s[36:37]
	global_load_dwordx4 v[228:231], v[78:79], off
	s_or_b64 exec, exec, s[0:1]
	v_lshl_add_u64 v[78:79], v[78:79], 0, s[34:35]
	s_and_b64 s[0:1], vcc, exec
	s_cselect_b32 s0, s12, s18
	v_lshl_add_u32 v226, s0, 6, v130
	v_ashrrev_i32_e32 v227, 31, v226
	v_lshlrev_b64 v[224:225], 8, v[226:227]
	v_lshl_add_u64 v[222:223], v[66:67], 0, v[224:225]
	global_load_dwordx4 v[232:235], v[222:223], off
	v_lshl_add_u64 v[222:223], v[68:69], 0, v[224:225]
	global_load_dwordx4 v[236:239], v[222:223], off
	v_lshlrev_b64 v[224:225], 11, v[226:227]
	v_lshl_add_u64 v[222:223], v[70:71], 0, v[224:225]
	global_load_dwordx4 v[240:243], v[222:223], off
	v_lshl_add_u64 v[222:223], v[72:73], 0, v[224:225]
	global_load_dwordx4 v[244:247], v[222:223], off
	v_lshl_add_u64 v[222:223], v[74:75], 0, v[224:225]
	global_load_dwordx4 v[248:251], v[222:223], off
	s_waitcnt vmcnt(0)
	v_and_b32_e32 v194, 1, v203
	v_sub_u32_e32 v200, 0, v194
	v_and_b32_e32 v200, 0x6060606, v200
	v_xor_b32_e32 v195, 0x5040100, v200
	v_mul_u32_u24_e32 v194, 0x8e, v194
	s_branch .LBB0_153
.LBB0_152:
	s_or_b64 exec, exec, s[0:1]
	v_lshlrev_b64 v[34:35], 10, v[80:81]
	v_add_f32_e32 v80, v149, v150
	v_max_f32_e32 v80, 0x179abe15, v80
	v_sub_f32_e32 v25, v33, v25
	v_rsq_f32_e32 v80, v80
	v_mul_f32_e32 v25, 0x3fb8aa3b, v25
	v_sub_f32_e32 v24, v32, v24
	v_exp_f32_e32 v25, v25
	v_mul_f32_e32 v24, 0x3fb8aa3b, v24
	v_sub_f32_e32 v23, v31, v23
	v_exp_f32_e32 v24, v24
	v_mul_f32_e32 v23, 0x3fb8aa3b, v23
	v_exp_f32_e32 v23, v23
	v_mul_f32_e32 v81, v145, v80
	v_mul_f32_e32 v145, 0xbfb8aa3b, v33
	v_mul_f32_e32 v25, v81, v25
	v_mul_f32_e64 v33, v81, -v40
	v_mul_f32_e32 v81, v144, v80
	v_mul_f32_e32 v40, v164, v143
	v_mul_f32_e32 v143, 0xbfb8aa3b, v32
	v_mul_f32_e32 v24, v81, v24
	v_mul_f32_e64 v32, v81, -v39
	v_mul_f32_e32 v81, v142, v80
	v_sub_f32_e32 v22, v30, v22
	v_mul_f32_e32 v39, v161, v141
	v_mul_f32_e32 v141, 0xbfb8aa3b, v31
	v_mul_f32_e32 v23, v81, v23
	v_mul_f32_e64 v31, v81, -v38
	v_mul_f32_e32 v81, v158, v139
	v_mul_f32_e32 v139, v140, v80
	v_mul_f32_e32 v140, 0xbfb8aa3b, v30
	v_mul_f32_e32 v22, 0x3fb8aa3b, v22
	v_exp_f32_e32 v140, v140
	v_exp_f32_e32 v22, v22
	v_mul_f32_e64 v30, v139, -v163
	v_sub_f32_e32 v21, v29, v21
	v_mul_f32_e32 v30, v30, v140
	v_mul_f32_e32 v22, v139, v22
	v_mul_f32_e32 v139, v165, v140
	v_mul_f32_e32 v140, 0xbfb8aa3b, v29
	v_mul_f32_e32 v21, 0x3fb8aa3b, v21
	v_exp_f32_e32 v140, v140
	v_exp_f32_e32 v21, v21
	v_mul_f32_e32 v138, v138, v80
	v_mul_f32_e64 v29, v138, -v159
	v_sub_f32_e32 v20, v28, v20
	v_mul_f32_e32 v21, v138, v21
	v_mul_f32_e32 v29, v29, v140
	v_mul_f32_e32 v138, v160, v140
	v_mul_f32_e32 v140, 0xbfb8aa3b, v28
	v_mul_f32_e32 v20, 0x3fb8aa3b, v20
	v_exp_f32_e32 v140, v140
	v_exp_f32_e32 v20, v20
	v_mul_f32_e32 v136, v136, v80
	v_sub_f32_e32 v19, v27, v19
	v_sub_f32_e32 v18, v26, v18
	v_mul_f32_e64 v28, v136, -v155
	v_mul_f32_e32 v19, 0x3fb8aa3b, v19
	v_mul_f32_e32 v18, 0x3fb8aa3b, v18
	v_mul_f32_e32 v20, v136, v20
	v_mul_f32_e32 v28, v28, v140
	v_mul_f32_e32 v136, v156, v140
	v_mul_f32_e32 v134, v134, v80
	v_mul_f32_e32 v140, 0xbfb8aa3b, v27
	v_exp_f32_e32 v19, v19
	v_mul_f32_e32 v80, v132, v80
	v_mul_f32_e32 v132, 0xbfb8aa3b, v26
	v_exp_f32_e32 v18, v18
	v_exp_f32_e32 v145, v145
	v_exp_f32_e32 v143, v143
	v_exp_f32_e32 v141, v141
	v_exp_f32_e32 v140, v140
	v_exp_f32_e32 v132, v132
	v_mul_f32_e32 v19, v134, v19
	v_mul_f32_e64 v27, v134, -v152
	v_mul_f32_e32 v18, v80, v18
	v_mul_f32_e64 v26, v80, -v148
	v_mul_f32_e32 v33, v33, v145
	v_mul_f32_e32 v37, v37, v145
	v_mul_f32_e32 v32, v32, v143
	v_mul_f32_e32 v36, v36, v143
	v_mul_f32_e32 v31, v31, v141
	v_mul_f32_e32 v38, v162, v141
	v_mul_f32_e32 v137, v157, v137
	v_mul_f32_e32 v135, v154, v135
	v_mul_f32_e32 v133, v147, v133
	v_mul_f32_e32 v27, v27, v140
	v_mul_f32_e32 v134, v153, v140
	v_mul_f32_e32 v131, v146, v131
	v_mul_f32_e32 v26, v26, v132
	v_mul_f32_e32 v80, v151, v132
	v_mul_f32_e32 v0, v41, v0
	v_cvt_pk_bf16_f32 v18, v18, v19
	v_cvt_pk_bf16_f32 v19, v20, v21
	v_cvt_pk_bf16_f32 v20, v22, v23
	v_cvt_pk_bf16_f32 v21, v24, v25
	ds_write_b128 v91, v[18:21]
; template <bool PA> ...
;     ...
;                 w.x = pk2(ah[0], ah[1]); w.y = pk2(ah[2], ah[3]); w.z = pk2(ah[4], ah[5]); w.w = pk2(ah[6], ah[7]); *(u32x4_t*)(MAT(0) + j * 72 + c8) = w;
;                 u32x4_t wb, wk;
;                 wb.x = pk2(bh[0], bh[1]); wb.y = pk2(bh[2], bh[3]); wb.z = pk2(bh[4], bh[5]); wb.w = pk2(bh[6], bh[7]); *(u32x4_t*)(MAT(1) + j * 72 + c8) = wb;
;                 wk.x = pk2(kh[0], kh[1]); wk.y = pk2(kh[2], kh[3]); wk.z = pk2(kh[4], kh[5]); wk.w = pk2(kh[6], kh[7]); *(u32x4_t*)(MAT(2) + j * 72 + c8) = wk;
;                 w.x = pk2(rh[0], rh[1]); w.y = pk2(rh[2], rh[3]); w.z = pk2(rh[4], rh[5]); w.w = pk2(rh[6], rh[7]); *(u32x4_t*)(MAT(3) + j * 72 + c8) = w;
;                 { const unsigned wba[4] = {wb.x, wb.y, wb.z, wb.w}, wka[4] = {wk.x, wk.y, wk.z, wk.w}, wva[4] = {vraw.x, vraw.y, vraw.z, vraw.w};
; #pragma unroll
;                   for (int q = 0; q < 4; ++q) { bf16* d4 = MAT(4) + (c8 + 2 * q) * 72 + j; bf16* d5 = MAT(5) + (c8 + 2 * q) * 72 + j; bf16* d6 = MAT(6) + (c8 + 2 * q) * 72 + j;
;                       d4[0] = (bf16)(wba[q] & 0xffffu); d4[72] = (bf16)(wba[q] >> 16); d5[0] = (bf16)(wka[q] & 0xffffu); d5[72] = (bf16)(wka[q] >> 16); d6[0] = (bf16)(wva[q] & 0xffffu); d6[72] = (bf16)(wva[q] >> 16); } }
;                 if (haveT) *(u32x4_t*)(MAT(9) + j * 72 + c8) = tld;
;                 st_rm(MAT(7), Sacc, mt, ntb, r16, kq);
;                 if (PA) st_rm(MAT(12), S2acc, mt, ntb, r16, kq);
;             }
;             __syncthreads();
;             f32x4_t Pacc[2], Tacc[2], Xacc[2], Yacc[2], tmp[2];
;             const f32x4_t z4 = (f32x4_t){0.f, 0.f, 0.f, 0.f};
;             Tacc[0] = z4; Tacc[1] = z4;
;             if (!haveT) {
;             Pacc[0] = z4; Pacc[1] = z4; mm2(Pacc, MAT(0), MAT(1), mt, ntb, r16, kq);
; #pragma unroll
;             for (int i = 0; i < 2; ++i)
; #pragma unroll
;                 for (int e = 0; e < 4; ++e) { const int t = 16 * mt + 4 * kq + e, s = 16 * (ntb + i) + r16; Pacc[i][e] = (s < t) ? Pacc[i][e] : 0.f; Tacc[i][e] = Pacc[i][e] + ((s == t) ? 1.f : 0.f); }
;             st_rm(MAT(8), Pacc, mt, ntb, r16, kq); st_tr(MAT(9), Pacc, mt, ntb, r16, kq);
;             }
;             tmp[0] = z4; tmp[1] = z4; mm2(tmp, MAT(0), MAT(2), mt, ntb, r16, kq);
; #pragma unroll
;             for (int i = 0; i < 2; ++i)
; #pragma unroll
	v_cvt_pk_bf16_f32 v18, v26, v27
	v_cvt_pk_bf16_f32 v19, v28, v29
	v_cvt_pk_bf16_f32 v20, v30, v31
	v_cvt_pk_bf16_f32 v21, v32, v33
	v_cvt_pk_bf16_f32 v22, v80, v134
	v_cvt_pk_bf16_f32 v23, v136, v138
	v_cvt_pk_bf16_f32 v24, v139, v38
	v_cvt_pk_bf16_f32 v25, v36, v37
	v_cvt_pk_bf16_f32 v26, v0, v131
	v_cvt_pk_bf16_f32 v27, v133, v135
	v_cvt_pk_bf16_f32 v28, v137, v81
	v_cvt_pk_bf16_f32 v29, v39, v40
	ds_write_b128 v91, v[18:21] offset:9216
	ds_write_b128 v91, v[22:25] offset:18432
	ds_write_b128 v91, v[26:29] offset:27648
	ds_write_b16 v117, v18 offset:36864
	ds_write_b16_d16_hi v117, v18 offset:37008
	ds_write_b16 v117, v22 offset:46080
	ds_write_b16_d16_hi v117, v22 offset:46224
	s_nop 0
	ds_write_b16 v117, v14 offset:55296
	ds_write_b16_d16_hi v117, v14 offset:55440
	ds_write_b16 v117, v19 offset:37152
	ds_write_b16_d16_hi v117, v19 offset:37296
	ds_write_b16 v117, v23 offset:46368
	ds_write_b16_d16_hi v117, v23 offset:46512
	ds_write_b16 v117, v15 offset:55584
	ds_write_b16_d16_hi v117, v15 offset:55728
	ds_write_b16 v176, v20 offset:37440
	ds_write_b16_d16_hi v176, v20 offset:37584
	ds_write_b16 v176, v24 offset:46656
	ds_write_b16_d16_hi v176, v24 offset:46800
	ds_write_b16 v176, v16 offset:55872
	ds_write_b16_d16_hi v176, v16 offset:56016
	ds_write_b16 v176, v21 offset:37728
	ds_write_b16_d16_hi v176, v21 offset:37872
	ds_write_b16 v176, v25 offset:46944
	ds_write_b16_d16_hi v176, v25 offset:47088
	ds_write_b16 v176, v17 offset:56160
	ds_write_b16_d16_hi v176, v17 offset:56304
	ds_write_b128 v101, v[10:13]
	v_cvt_pk_bf16_f32 v0, v6, v7
	v_cvt_pk_bf16_f32 v10, v8, v9
	s_nop 1
	v_mov_b32_dpp v200, v0 quad_perm:[1,0,3,2] row_mask:0xf bank_mask:0xf
	v_add_u32_e32 v177, v194, v87
	v_perm_b32 v200, v200, v0, v195
	ds_write_b32 v177, v200 offset:64512
	s_nop 1
	v_mov_b32_dpp v200, v10 quad_perm:[1,0,3,2] row_mask:0xf bank_mask:0xf
	v_perm_b32 v200, v200, v10, v195
	ds_write_b32 v177, v200 offset:64800
	v_cvt_pk_bf16_f32 v0, v2, v3
	v_cvt_pk_bf16_f32 v10, v4, v5
	s_nop 1
	v_mov_b32_dpp v200, v0 quad_perm:[1,0,3,2] row_mask:0xf bank_mask:0xf
	v_perm_b32 v200, v200, v0, v195
	ds_write_b32 v177, v200 offset:64544
	s_nop 1
	v_mov_b32_dpp v200, v10 quad_perm:[1,0,3,2] row_mask:0xf bank_mask:0xf
	v_perm_b32 v200, v200, v10, v195
	ds_write_b32 v177, v200 offset:64832
	s_waitcnt lgkmcnt(0)
	s_barrier
	ds_read_b128 v[178:181], v92
	ds_read_b128 v[182:185], v89 offset:18432
	ds_read_b128 v[186:189], v89 offset:20736
	ds_read_b128 v[190:193], v92 offset:64
	ds_read_b128 v[204:207], v89 offset:18496
	ds_read_b128 v[208:211], v89 offset:20800
	ds_read_b128 v[212:215], v92 offset:27648
	ds_read_b128 v[216:219], v89 offset:9216
	ds_read_b128 v[220:223], v89 offset:11520
	ds_read_b128 v[224:227], v92 offset:27712
	s_nop 0
	s_nop 0
	s_nop 0
	s_waitcnt lgkmcnt(8)
	v_mfma_f32_16x16x32_bf16 v[14:17], v[178:181], v[182:185], 0
	ds_read_b128 v[182:185], v89 offset:9280
	s_add_i32 s12, s12, 1
	s_add_i32 s18, s18, -1
	v_lshl_add_u64 v[78:79], v[78:79], 0, s[34:35]
	s_waitcnt lgkmcnt(8)
	v_mfma_f32_16x16x32_bf16 v[10:13], v[178:181], v[186:189], 0
	ds_read_b128 v[178:181], v89 offset:11584
	ds_read_b128 v[186:189], v92 offset:27648
	s_nop 0
	s_nop 0
	s_cmp_ge_i32 s12, s13
	s_waitcnt lgkmcnt(8)
	v_mfma_f32_16x16x32_bf16 v[14:17], v[190:193], v[204:207], v[14:17]
	ds_read_b128 v[204:207], v89 offset:18432
	s_nop 0
	s_waitcnt lgkmcnt(8)
	v_mfma_f32_16x16x32_bf16 v[10:13], v[190:193], v[208:211], v[10:13]
	ds_read_b128 v[190:193], v89 offset:20736
	ds_read_b128 v[208:211], v92 offset:27712
	s_nop 4
	v_cndmask_b32_e64 v0, 0, v14, s[62:63]
	v_cndmask_b32_e64 v14, v15, 0, s[64:65]
	v_cndmask_b32_e64 v15, 0, v16, s[66:67]
	v_cndmask_b32_e64 v16, 0, v17, s[68:69]
	v_cndmask_b32_e64 v10, 0, v10, s[70:71]
	v_cndmask_b32_e64 v11, v11, 0, s[72:73]
	v_cvt_pk_bf16_f32 v0, v0, v14
	v_cndmask_b32_e64 v12, 0, v12, s[74:75]
	v_cndmask_b32_e64 v13, 0, v13, s[76:77]
	v_cvt_pk_bf16_f32 v14, v15, v16
	s_nop 1
	v_mov_b32_dpp v200, v0 quad_perm:[1,0,3,2] row_mask:0xf bank_mask:0xf
	v_add_u32_e32 v177, v194, v102
	v_perm_b32 v200, v200, v0, v195
	ds_write_b32 v177, v200
	s_nop 1
	v_mov_b32_dpp v200, v14 quad_perm:[1,0,3,2] row_mask:0xf bank_mask:0xf
	v_perm_b32 v200, v200, v14, v195
	ds_write_b32 v177, v200 offset:288
	v_cvt_pk_bf16_f32 v0, v10, v11
	v_cvt_pk_bf16_f32 v10, v12, v13
	s_nop 1
	v_mov_b32_dpp v200, v0 quad_perm:[1,0,3,2] row_mask:0xf bank_mask:0xf
	v_perm_b32 v200, v200, v0, v195
	ds_write_b32 v177, v200 offset:32
	s_nop 1
	v_mov_b32_dpp v200, v10 quad_perm:[1,0,3,2] row_mask:0xf bank_mask:0xf
	v_perm_b32 v200, v200, v10, v195
	ds_write_b32 v177, v200 offset:320
	s_nop 0
	s_nop 0
	s_nop 0
	s_waitcnt lgkmcnt(0)
	v_mfma_f32_16x16x32_bf16 v[14:17], v[212:215], v[216:219], 0
	ds_read_b128 v[216:219], v89 offset:18496
	s_waitcnt lgkmcnt(1)
	v_mfma_f32_16x16x32_bf16 v[10:13], v[212:215], v[220:223], 0
	ds_read_b128 v[212:215], v89 offset:20800
	ds_read_b128 v[220:223], v92
	s_nop 0
	s_nop 0
	s_waitcnt lgkmcnt(3)
	v_mfma_f32_16x16x32_bf16 v[14:17], v[224:227], v[182:185], v[14:17]
	ds_read_b128 v[182:185], v89 offset:64512
	s_nop 0
	s_waitcnt lgkmcnt(4)
; template <bool PA> ...
;     ...
;             tmp[0] = z4; tmp[1] = z4; mm2(tmp, MAT(3), MAT(2), mt, ntb, r16, kq);
; #pragma unroll
;             for (int i = 0; i < 2; ++i)
; #pragma unroll
;                 for (int e = 0; e < 4; ++e) { const int t = 16 * mt + 4 * kq + e, s = 16 * (ntb + i) + r16; tmp[i][e] = (s <= t) ? tmp[i][e] : 0.f; }
;             st_rm(MAT(12), tmp, mt, ntb, r16, kq);
;             }
;             Xacc[0] = z4; Xacc[1] = z4; mm2(Xacc, MAT(0), MAT(7), mt, ntb, r16, kq);
;             Yacc[0] = z4; Yacc[1] = z4; if (!PA) mm2(Yacc, MAT(3), MAT(7), mt, ntb, r16, kq);
;             __syncthreads();
;             if (!haveT) {
;             tmp[0] = z4; tmp[1] = z4; mm2(tmp, MAT(8), MAT(9), mt, ntb, r16, kq);
;             st_rm(MAT(0), tmp, mt, ntb, r16, kq); st_tr(MAT(1), tmp, mt, ntb, r16, kq); st_rm(MAT(2), Tacc, mt, ntb, r16, kq);
;             __syncthreads();
; #pragma unroll
;             for (int i = 1; i <= 5; ++i) {
;                 bf16* Pc = (i & 1) ? MAT(0) : MAT(8); bf16* PcT = (i & 1) ? MAT(1) : MAT(9); bf16* Pn = (i & 1) ? MAT(8) : MAT(0); bf16* PnT = (i & 1) ? MAT(9) : MAT(1);
;                 bf16* Tc = (i & 1) ? MAT(2) : MAT(3); bf16* Tn = (i & 1) ? MAT(3) : MAT(2);
;                 mm2(Tacc, Tc, PcT, mt, ntb, r16, kq);
;                 if (i < 5) { tmp[0] = z4; tmp[1] = z4; mm2(tmp, Pc, PcT, mt, ntb, r16, kq); st_rm(Pn, tmp, mt, ntb, r16, kq); st_tr(PnT, tmp, mt, ntb, r16, kq); }
;                 st_rm(Tn, Tacc, mt, ntb, r16, kq);
;                 __syncthreads();
;             }
;             }
;             if (PA && tlow) *(u32x4_t*)(tbuf + ((size_t)strm * NCHA + p) * 2304 + tunit * 8) = *(const u32x4_t*)(MAT(3) + j * 72 + c8);
;             const bf16* Tm = haveT ? MAT(9) : MAT(3);
;             mm2(Xacc, MAT(10), MAT(6), mt, ntb, r16, kq);
;             st_tr(MAT(7), Xacc, mt, ntb, r16, kq);
;             if (PA) st_tr(MAT(11), X2acc, mt, ntb, r16, kq);
;             __syncthreads();
	v_mfma_f32_16x16x32_bf16 v[10:13], v[224:227], v[178:181], v[10:13]
	ds_read_b128 v[178:181], v105
	ds_read_b128 v[224:227], v92 offset:64
	s_nop 4
	v_cndmask_b32_e64 v0, v14, 0, s[64:65]
	v_cndmask_b32_e64 v14, v15, 0, s[78:79]
	v_cndmask_b32_e64 v15, v16, 0, s[80:81]
	v_cndmask_b32_e64 v16, v17, 0, s[82:83]
	v_cndmask_b32_e64 v10, v10, 0, s[72:73]
	v_cndmask_b32_e64 v11, v11, 0, s[84:85]
	v_cvt_pk_bf16_f32 v0, v0, v14
	v_cndmask_b32_e64 v12, v12, 0, s[86:87]
	v_cndmask_b32_e64 v13, v13, 0, s[88:89]
	v_cvt_pk_bf16_f32 v14, v15, v16
	s_nop 1
	v_mov_b32_dpp v200, v0 quad_perm:[1,0,3,2] row_mask:0xf bank_mask:0xf
	v_add_u32_e32 v177, v194, v103
	v_perm_b32 v200, v200, v0, v195
	ds_write_b32 v177, v200
	s_nop 1
	v_mov_b32_dpp v200, v14 quad_perm:[1,0,3,2] row_mask:0xf bank_mask:0xf
	v_perm_b32 v200, v200, v14, v195
	ds_write_b32 v177, v200 offset:288
	v_cvt_pk_bf16_f32 v0, v10, v11
	v_cvt_pk_bf16_f32 v10, v12, v13
	s_nop 1
	v_mov_b32_dpp v200, v0 quad_perm:[1,0,3,2] row_mask:0xf bank_mask:0xf
	v_perm_b32 v200, v200, v0, v195
	ds_write_b32 v177, v200 offset:32
	s_nop 1
	v_mov_b32_dpp v200, v10 quad_perm:[1,0,3,2] row_mask:0xf bank_mask:0xf
	v_perm_b32 v200, v200, v10, v195
	ds_write_b32 v177, v200 offset:320
	s_nop 0
	s_nop 0
	s_nop 0
	s_waitcnt lgkmcnt(0)
	v_mfma_f32_16x16x32_bf16 v[14:17], v[186:189], v[204:207], 0
	ds_read_b128 v[204:207], v92 offset:27648
	s_waitcnt lgkmcnt(1)
	v_mfma_f32_16x16x32_bf16 v[10:13], v[186:189], v[190:193], 0
	s_nop 0
	s_nop 0
	s_waitcnt lgkmcnt(1)
	v_mfma_f32_16x16x32_bf16 v[14:17], v[208:211], v[216:219], v[14:17]
	s_nop 0
	s_waitcnt lgkmcnt(1)
	v_mfma_f32_16x16x32_bf16 v[10:13], v[208:211], v[212:215], v[10:13]
	s_nop 4
	v_cndmask_b32_e64 v0, v14, 0, s[64:65]
	v_cndmask_b32_e64 v14, v15, 0, s[78:79]
	v_cndmask_b32_e64 v15, v16, 0, s[80:81]
	v_cndmask_b32_e64 v16, v17, 0, s[82:83]
	v_cndmask_b32_e64 v10, v10, 0, s[72:73]
	v_cndmask_b32_e64 v11, v11, 0, s[84:85]
	v_cvt_pk_bf16_f32 v0, v0, v14
	v_cndmask_b32_e64 v12, v12, 0, s[86:87]
	v_cndmask_b32_e64 v13, v13, 0, s[88:89]
	v_cvt_pk_bf16_f32 v14, v15, v16
	s_nop 1
	v_mov_b32_dpp v200, v0 quad_perm:[1,0,3,2] row_mask:0xf bank_mask:0xf
	v_add_u32_e32 v177, v194, v104
	v_perm_b32 v200, v200, v0, v195
	ds_write_b32 v177, v200
	s_nop 1
	v_mov_b32_dpp v200, v14 quad_perm:[1,0,3,2] row_mask:0xf bank_mask:0xf
	v_perm_b32 v200, v200, v14, v195
	ds_write_b32 v177, v200 offset:288
	v_cvt_pk_bf16_f32 v0, v10, v11
	v_cvt_pk_bf16_f32 v10, v12, v13
	s_nop 1
	v_mov_b32_dpp v200, v0 quad_perm:[1,0,3,2] row_mask:0xf bank_mask:0xf
	v_perm_b32 v200, v200, v0, v195
	ds_write_b32 v177, v200 offset:32
	s_nop 1
	v_mov_b32_dpp v200, v10 quad_perm:[1,0,3,2] row_mask:0xf bank_mask:0xf
	v_perm_b32 v200, v200, v10, v195
	ds_write_b32 v177, v200 offset:320
	s_nop 0
	s_nop 0
	s_nop 0
	s_nop 0
	ds_read_b128 v[30:33], v89 offset:64576
	ds_read_b128 v[36:39], v106
	s_waitcnt lgkmcnt(2)
	v_mfma_f32_16x16x32_bf16 v[18:21], v[220:223], v[182:185], 0
	s_waitcnt lgkmcnt(2)
	v_mfma_f32_16x16x32_bf16 v[10:13], v[220:223], v[178:181], 0
	s_waitcnt lgkmcnt(1)
	v_mfma_f32_16x16x32_bf16 v[18:21], v[224:227], v[30:33], v[18:21]
	s_waitcnt lgkmcnt(0)
	v_mfma_f32_16x16x32_bf16 v[10:13], v[224:227], v[36:39], v[10:13]
	s_nop 0
	s_waitcnt lgkmcnt(0)
	v_mfma_f32_16x16x32_bf16 v[14:17], v[204:207], v[182:185], 0
	v_mfma_f32_16x16x32_bf16 v[22:25], v[204:207], v[178:181], 0
	ds_read_b128 v[26:29], v92 offset:27712
	s_waitcnt lgkmcnt(0)
	s_barrier
	ds_read_b128 v[178:181], v107
	ds_read_b128 v[182:185], v89 offset:55296
	ds_read_b128 v[186:189], v89 offset:57600
	ds_read_b128 v[190:193], v107 offset:64
	ds_read_b128 v[204:207], v89 offset:55360
	ds_read_b128 v[208:211], v89 offset:57664
	v_mfma_f32_16x16x32_bf16 v[14:17], v[26:29], v[30:33], v[14:17]
	v_mfma_f32_16x16x32_bf16 v[22:25], v[26:29], v[36:39], v[22:25]
	s_nop 0
	s_nop 0
	s_waitcnt lgkmcnt(4)
	v_mfma_f32_16x16x32_bf16 v[18:21], v[178:181], v[182:185], v[18:21]
	s_nop 0
	s_waitcnt lgkmcnt(3)
	v_mfma_f32_16x16x32_bf16 v[10:13], v[178:181], v[186:189], v[10:13]
	s_nop 0
	s_nop 0
	s_waitcnt lgkmcnt(1)
	v_mfma_f32_16x16x32_bf16 v[18:21], v[190:193], v[204:207], v[18:21]
	s_nop 0
	s_waitcnt lgkmcnt(0)
	v_mfma_f32_16x16x32_bf16 v[10:13], v[190:193], v[208:211], v[10:13]
	s_nop 4
	v_cvt_pk_bf16_f32 v18, v18, v19
	v_cvt_pk_bf16_f32 v19, v20, v21
	ds_write_b64 v108, v[18:19] offset:64512
	v_cvt_pk_bf16_f32 v10, v10, v11
	v_cvt_pk_bf16_f32 v11, v12, v13
	ds_write_b64 v109, v[10:11]
	s_waitcnt lgkmcnt(0)
	s_barrier
; template <bool PA> ...
;     ...
;             const bf16* Tm = haveT ? MAT(9) : MAT(3);
;             mm2(Xacc, MAT(10), MAT(6), mt, ntb, r16, kq);
;             st_tr(MAT(7), Xacc, mt, ntb, r16, kq);
;             if (PA) st_tr(MAT(11), X2acc, mt, ntb, r16, kq);
;             __syncthreads();
;             tmp[0] = z4; tmp[1] = z4; mm2(tmp, Tm, MAT(7), mt, ntb, r16, kq);
;             st_tr(MAT(8), tmp, mt, ntb, r16, kq);
;             if (PA) { tmp[0] = z4; tmp[1] = z4; mm2(tmp, MAT(3), MAT(11), mt, ntb, r16, kq); st_tr(MAT(12), tmp, mt, ntb, r16, kq); }
;             __syncthreads();
;             if (!PA) { mm2(Yacc, MAT(11), MAT(8), mt, ntb, r16, kq); mm2(Yacc, MAT(12), MAT(6), mt, ntb, r16, kq);
;             st_rm(MAT(7), Yacc, mt, ntb, r16, kq); }
;             if (PA) mm2(S2acc, MAT(12), MAT(4), mt, ntb, r16, kq);
;             mm2(Sacc, MAT(8), MAT(4), mt, ntb, r16, kq); mm2(Sacc, MAT(6), MAT(5), mt, ntb, r16, kq);
; #pragma unroll
;             for (int i = 0; i < 2; ++i) { const float wk = wc[16 * (ntb + i) + r16];
; #pragma unroll
;                 for (int e = 0; e < 4; ++e) { Sacc[i][e] *= wk; S2acc[i][e] *= wk; } }
;             __syncthreads();
;             if (!PA) { const size_t orow = cbase + (d ? 63 - j : j); *(u32x4_t*)(Op + orow * 1024 + hc8) = *(const u32x4_t*)(MAT(7) + j * 72 + c8); }
	ds_read_b128 v[178:181], v110
	ds_read_b128 v[182:185], v89 offset:64512
	ds_read_b128 v[186:189], v105
	ds_read_b128 v[190:193], v110 offset:64
	ds_read_b128 v[204:207], v89 offset:64576
	ds_read_b128 v[208:211], v106
	s_nop 0
	s_nop 0
	s_nop 0
	s_waitcnt lgkmcnt(4)
	v_mfma_f32_16x16x32_bf16 v[18:21], v[178:181], v[182:185], 0
	s_waitcnt lgkmcnt(3)
	v_mfma_f32_16x16x32_bf16 v[10:13], v[178:181], v[186:189], 0
	s_nop 0
	s_nop 0
	s_waitcnt lgkmcnt(1)
	v_mfma_f32_16x16x32_bf16 v[18:21], v[190:193], v[204:207], v[18:21]
	s_nop 0
	s_waitcnt lgkmcnt(0)
	v_mfma_f32_16x16x32_bf16 v[10:13], v[190:193], v[208:211], v[10:13]
	v_mov_b32_e32 v26, v190
	v_mov_b32_e32 v27, v191
	v_mov_b32_e32 v28, v192
	v_mov_b32_e32 v29, v193
	v_mov_b32_e32 v30, v208
	v_mov_b32_e32 v31, v209
	v_mov_b32_e32 v32, v210
	v_mov_b32_e32 v33, v211
	s_nop 4
	v_cvt_pk_bf16_f32 v18, v18, v19
	v_cvt_pk_bf16_f32 v19, v20, v21
	ds_write_b64 v111, v[18:19]
	v_cvt_pk_bf16_f32 v10, v10, v11
	v_cvt_pk_bf16_f32 v11, v12, v13
	ds_write_b64 v111, v[10:11] offset:2304
	s_waitcnt lgkmcnt(0)
	s_barrier
	ds_read_b128 v[178:181], v112
	ds_read_b128 v[182:185], v113
	ds_read_b128 v[186:189], v113 offset:2304
	ds_read_b128 v[190:193], v112 offset:64
	ds_read_b128 v[204:207], v113 offset:64
	ds_read_b128 v[208:211], v113 offset:2368
	ds_read_b128 v[212:215], v114
	ds_read_b128 v[216:219], v89 offset:55296
	ds_read_b128 v[220:223], v89 offset:57600
	ds_read_b128 v[224:227], v114 offset:64
	s_nop 0
	s_nop 0
	s_waitcnt lgkmcnt(8)
	v_mfma_f32_16x16x32_bf16 v[14:17], v[178:181], v[182:185], v[14:17]
	ds_read_b128 v[182:185], v89 offset:55360
	s_nop 0
	s_waitcnt lgkmcnt(8)
	v_mfma_f32_16x16x32_bf16 v[10:13], v[178:181], v[186:189], v[22:25]
	ds_read_b128 v[178:181], v89 offset:57664
	ds_read_b128 v[186:189], v115
	s_nop 0
	s_nop 1
	s_nop 0
	s_waitcnt lgkmcnt(8)
	v_mfma_f32_16x16x32_bf16 v[14:17], v[190:193], v[204:207], v[14:17]
	ds_read_b128 v[204:207], v89 offset:36864
	s_nop 0
	s_waitcnt lgkmcnt(8)
	v_mfma_f32_16x16x32_bf16 v[10:13], v[190:193], v[208:211], v[10:13]
	ds_read_b128 v[190:193], v89 offset:39168
	ds_read_b128 v[208:211], v115 offset:64
	s_nop 0
	s_nop 0
	s_waitcnt lgkmcnt(8)
	v_mfma_f32_16x16x32_bf16 v[14:17], v[212:215], v[216:219], v[14:17]
	ds_read_b128 v[216:219], v89 offset:36928
	s_nop 0
	s_waitcnt lgkmcnt(8)
	v_mfma_f32_16x16x32_bf16 v[10:13], v[212:215], v[220:223], v[10:13]
	ds_read_b128 v[212:215], v89 offset:39232
	ds_read_b128 v[220:223], v92 offset:55296
	s_nop 0
	s_nop 0
	s_waitcnt lgkmcnt(8)
	v_mfma_f32_16x16x32_bf16 v[14:17], v[224:227], v[182:185], v[14:17]
	ds_read_b128 v[182:185], v89 offset:46080
	s_nop 0
	s_waitcnt lgkmcnt(8)
	v_mfma_f32_16x16x32_bf16 v[10:13], v[224:227], v[178:181], v[10:13]
	v_mov_b32_e32 v18, v224
	v_mov_b32_e32 v19, v225
	v_mov_b32_e32 v20, v226
	v_mov_b32_e32 v21, v227
	v_mov_b32_e32 v22, v178
	v_mov_b32_e32 v23, v179
	v_mov_b32_e32 v24, v180
	v_mov_b32_e32 v25, v181
	ds_read_b128 v[178:181], v89 offset:48384
	ds_read_b128 v[224:227], v92 offset:55360
	s_nop 4
	v_cvt_pk_bf16_f32 v0, v14, v15
	v_cvt_pk_bf16_f32 v14, v16, v17
	s_nop 1
	v_mov_b32_dpp v200, v0 quad_perm:[1,0,3,2] row_mask:0xf bank_mask:0xf
	v_add_u32_e32 v177, v194, v87
	v_perm_b32 v200, v200, v0, v195
	ds_write_b32 v177, v200 offset:64512
	s_nop 1
	v_mov_b32_dpp v200, v14 quad_perm:[1,0,3,2] row_mask:0xf bank_mask:0xf
	v_perm_b32 v200, v200, v14, v195
	ds_write_b32 v177, v200 offset:64800
	v_cvt_pk_bf16_f32 v0, v10, v11
	v_cvt_pk_bf16_f32 v10, v12, v13
	s_nop 1
	v_mov_b32_dpp v200, v0 quad_perm:[1,0,3,2] row_mask:0xf bank_mask:0xf
	v_perm_b32 v200, v200, v0, v195
	ds_write_b32 v177, v200 offset:64544
	s_nop 1
	v_mov_b32_dpp v200, v10 quad_perm:[1,0,3,2] row_mask:0xf bank_mask:0xf
	v_perm_b32 v200, v200, v10, v195
	ds_write_b32 v177, v200 offset:64832
	s_nop 0
	s_nop 0
	s_waitcnt lgkmcnt(0)
	v_mfma_f32_16x16x32_bf16 v[6:9], v[186:189], v[204:207], v[6:9]
	ds_read_b128 v[204:207], v89 offset:46144
	s_nop 0
	s_waitcnt lgkmcnt(1)
	v_mfma_f32_16x16x32_bf16 v[2:5], v[186:189], v[190:193], v[2:5]
	ds_read_b128 v[186:189], v89 offset:48448
	s_nop 0
	s_nop 0
	s_waitcnt lgkmcnt(2)
	v_mfma_f32_16x16x32_bf16 v[6:9], v[208:211], v[216:219], v[6:9]
	s_nop 0
	s_waitcnt lgkmcnt(2)
	v_mfma_f32_16x16x32_bf16 v[2:5], v[208:211], v[212:215], v[2:5]
	s_nop 0
	s_nop 0
	s_waitcnt lgkmcnt(2)
	v_mfma_f32_16x16x32_bf16 v[6:9], v[220:223], v[182:185], v[6:9]
	s_nop 0
	s_waitcnt lgkmcnt(2)
	v_mfma_f32_16x16x32_bf16 v[2:5], v[220:223], v[178:181], v[2:5]
	s_nop 0
	s_nop 0
	ds_read_b32 v0, v127
	s_waitcnt lgkmcnt(2)
	v_mfma_f32_16x16x32_bf16 v[6:9], v[224:227], v[204:207], v[6:9]
	s_nop 0
	s_waitcnt lgkmcnt(0)
	v_mfma_f32_16x16x32_bf16 v[2:5], v[224:227], v[186:189], v[2:5]
	v_mov_b32_e32 v16, v188
	v_mov_b32_e32 v17, v189
	s_nop 4
	v_mul_f32_e64 v6, v6, v0
	v_mul_f32_e64 v7, v7, v0
	v_pk_mul_f32 v[8:9], v[8:9], v[0:1] op_sel_hi:[1,0]
	ds_read_b32 v0, v128
	s_waitcnt lgkmcnt(0)
	s_barrier
	ds_read_b128 v[10:13], v91 offset:64512
	v_pk_mul_f32 v[2:3], v[2:3], v[0:1] op_sel_hi:[1,0]
	v_pk_mul_f32 v[4:5], v[4:5], v[0:1] op_sel_hi:[1,0]
	v_lshl_add_u64 v[14:15], v[34:35], 1, v[76:77]
	s_waitcnt lgkmcnt(0)
	global_store_dwordx4 v[14:15], v[10:13], off
	s_cbranch_scc1 .LBB0_128

; template <bool PA> ...
;     ...
;         const int g = item % G, strm = item / G; const int p0 = g == 0 ? 0 : 1 + 32 * g, p1 = 33 + 32 * g;
;         const bool haveT = !PA;
;         const int d = strm & 1, head = (strm >> 1) & 15, sq = strm >> 5; const int seqbase = sq * 8256; const int hc8 = head * 64 + c8;
;         bf16* Op = d ? OBb : OFb;
;         const float* w0 = a->in[15] + d * 1024; const float* w2 = a->in[17] + (size_t)d * 64 * 1024; const float* a0 = a->in[18] + d * 1024; const float* a2 = a->in[20] + (size_t)d * 64 * 1024;
;         __syncthreads();
;         if (tid < 320) { const int wch = tid >> 6, cc = tid & 63; const float* src = wch == 0 ? w0 : (wch == 1 ? a0 : (wch == 2 ? a->in[23] : (wch == 3 ? a->in[24] : a->in[25]))); cst[tid] = src[head * 64 + cc]; }
;         for (int i = tid; i < 4096; i += 512) { const int l = i >> 6, cc = i & 63; w2T[cc * 72 + l] = (bf16)f2bf(w2[(size_t)l * 1024 + head * 64 + cc]); a2T[cc * 72 + l] = (bf16)f2bf(a2[(size_t)l * 1024 + head * 64 + cc]); }
;         f32x4_t Sacc[2], S2acc[2]; Sacc[0] = (f32x4_t){0.f, 0.f, 0.f, 0.f}; Sacc[1] = Sacc[0];
; #pragma unroll
;         for (int i = 0; i < 2; ++i)
; #pragma unroll
;             for (int e = 0; e < 4; ++e) S2acc[i][e] = (16 * mt + 4 * kq + e == 16 * (ntb + i) + r16) ? 1.f : 0.f;
;         __syncthreads();
;         if (!PA) {
;             for (int gg = 0; gg < g; ++gg) {
;                 const float* Psi = segm + (size_t)(strm * G + gg) * 8192; const float* Phi = Psi + 4096;
;                 { const f32x4_t q0 = *(const f32x4_t*)(Phi + j * 64 + c8), q1 = *(const f32x4_t*)(Phi + j * 64 + c8 + 4);
; #pragma unroll
;                   for (int e = 0; e < 4; ++e) { MAT(1)[(c8 + e) * 72 + j] = (bf16)f2bf(q0[e]); MAT(1)[(c8 + 4 + e) * 72 + j] = (bf16)f2bf(q1[e]); } }
;                 st_rm(MAT(0), Sacc, mt, ntb, r16, kq);
;                 __syncthreads();
; #pragma unroll
;                 for (int i = 0; i < 2; ++i)
; #pragma unroll
;                     for (int e = 0; e < 4; ++e) Sacc[i][e] = Psi[(16 * mt + 4 * kq + e) * 64 + 16 * (ntb + i) + r16];
;                 mm2(Sacc, MAT(0), MAT(1), mt, ntb, r16, kq);
;                 __syncthreads();
;             }
;         }
;         for (int p = p0; p < p1; ++p) {
;             const int cidx = d ? nch - 1 - p : p; const int cbase = seqbase + cidx * 64;
.LBB0_211:
	s_or_b64 exec, exec, s[12:13]
	s_mul_i32 s12, s15, s78
	s_sub_i32 s12, s82, s12
	s_lshl_b32 s21, s12, 5
	s_or_b32 s13, s21, 1
	s_cmp_lg_u32 s12, 0
	s_cselect_b32 s20, s13, 0
	s_add_i32 s21, s21, 33
	v_mov_b32_e32 v9, 0
	s_cmp_lt_i32 s20, s21
	v_mov_b32_e32 v8, v9
	v_mov_b32_e32 v7, v9
	v_mov_b32_e32 v6, v9
	v_mov_b32_e32 v5, v9
	v_mov_b32_e32 v4, v9
	v_mov_b32_e32 v3, v9
	v_mov_b32_e32 v2, v9
	v_mov_b32_e32 v17, v143
	v_mov_b32_e32 v16, v142
	v_mov_b32_e32 v15, v141
	v_mov_b32_e32 v14, v140
	v_mov_b32_e32 v13, v139
	v_mov_b32_e32 v12, v138
	v_mov_b32_e32 v11, v137
	v_mov_b32_e32 v10, v136
	s_waitcnt lgkmcnt(0)
	s_barrier
	s_cbranch_scc0 .LBB0_193
	s_lshr_b32 s12, s15, 5
	s_cmp_eq_u32 s24, 0
	s_cselect_b64 s[74:75], -1, 0
	s_mulk_i32 s12, 0x2040
	v_cndmask_b32_e64 v2, v107, v104, s[74:75]
	s_waitcnt vmcnt(44)
	v_add_u32_e32 v160, s12, v2
	s_lshl_b32 s24, s24, 7
	s_mul_hi_i32 s12, s15, s91
	s_mul_i32 s15, s15, s91
	s_ashr_i32 s13, s20, 31
	s_add_u32 s15, s15, s20
	v_or_b32_e32 v0, s80, v105
	s_addc_u32 s12, s12, s13
	v_lshl_add_u64 v[90:91], v[66:67], 0, s[24:25]
	v_lshl_add_u64 v[92:93], v[70:71], 0, s[24:25]
	v_lshlrev_b32_e32 v0, 1, v0
	s_mul_i32 s24, s12, 0x1200
	v_mad_u64_u32 v[100:101], s[12:13], s15, v199, v[72:73]
	v_mov_b32_e32 v8, 0
	v_lshl_add_u64 v[94:95], s[0:1], 0, v[0:1]
	v_lshl_add_u64 v[96:97], s[18:19], 0, v[0:1]
	v_lshl_add_u64 v[98:99], s[22:23], 0, v[0:1]
	v_add_u32_e32 v101, s24, v101
	s_sub_i32 s24, s79, s20
	v_mov_b32_e32 v10, v136
	v_mov_b32_e32 v11, v137
	v_mov_b32_e32 v12, v138
	v_mov_b32_e32 v13, v139
	v_mov_b32_e32 v14, v140
	v_mov_b32_e32 v15, v141
	v_mov_b32_e32 v16, v142
	v_mov_b32_e32 v17, v143
	v_mov_b32_e32 v0, 0
	v_mov_b32_e32 v2, 0
	v_mov_b32_e32 v3, v8
	v_mov_b32_e32 v4, v8
	v_mov_b32_e32 v5, v8
	v_mov_b32_e32 v6, 0
	v_mov_b32_e32 v7, v8
	v_mov_b32_e32 v9, v8
	s_and_b64 s[12:13], s[74:75], exec
	s_cselect_b32 s12, s20, s24
	v_lshl_add_u32 v226, s12, 6, v160
	v_ashrrev_i32_e32 v227, 31, v226
	v_lshlrev_b64 v[224:225], 8, v[226:227]
	v_lshl_add_u64 v[222:223], v[90:91], 0, v[224:225]
	global_load_dwordx4 v[232:235], v[222:223], off
	v_lshl_add_u64 v[222:223], v[92:93], 0, v[224:225]
	global_load_dwordx4 v[236:239], v[222:223], off
	v_lshlrev_b64 v[224:225], 11, v[226:227]
	v_lshl_add_u64 v[222:223], v[94:95], 0, v[224:225]
	global_load_dwordx4 v[240:243], v[222:223], off
	v_lshl_add_u64 v[222:223], v[96:97], 0, v[224:225]
	global_load_dwordx4 v[244:247], v[222:223], off
	v_lshl_add_u64 v[222:223], v[98:99], 0, v[224:225]
	global_load_dwordx4 v[248:251], v[222:223], off
	s_waitcnt vmcnt(0)
	v_and_b32_e32 v194, 1, v203
	v_sub_u32_e32 v200, 0, v194
	v_and_b32_e32 v200, 0x6060606, v200
	v_xor_b32_e32 v195, 0x5040100, v200
	v_mul_u32_u24_e32 v194, 0x8e, v194

; __device__ __forceinline__ float sigmoidf_(float x) { return __builtin_amdgcn_rcpf(1.0f + __expf(-x)); }
; template <bool PA> ...
;     ...
;                 const float inv = rsqrtf(fmaxf(ss, 1e-24f));
; #pragma unroll
;                 for (int e = 0; e < 8; ++e) { av[e] = sigmoidf_(aa[e]); lw[e] = -0.6065306597f * sigmoidf_(z[e]); kd[e] = kv[e] * (1.0f + (av[e] - 1.0f) * cst[192 + c8 + e]); kk[e] *= inv; bsum += rv[e] * kd[e] * cst[256 + c8 + e]; }
;                 bsum += __shfl_xor(bsum, 1); bsum += __shfl_xor(bsum, 2); bsum += __shfl_xor(bsum, 4);
;                 if (!PA && part == 0) beta[((size_t)d * SLAB + row) * 16 + head] = bsum;
;                 *(f32x4_t*)(cumb + j * 64 + c8) = (f32x4_t){lw[0], lw[1], lw[2], lw[3]}; *(f32x4_t*)(cumb + j * 64 + c8 + 4) = (f32x4_t){lw[4], lw[5], lw[6], lw[7]};
;             }
;             __syncthreads();
;             { const int c = tid & 63, sg = tid >> 6; float run = 0.f;
; #pragma unroll
;               for (int i = 0; i < 8; ++i) { run += cumb[(8 * sg + i) * 64 + c]; cumb[(8 * sg + i) * 64 + c] = run; }
;               segtot[sg * 64 + c] = run; }
;             __syncthreads();
;             { const int c = tid & 63, sg = tid >> 6; float off = 0.f;
; #pragma unroll
;               for (int s = 0; s < 7; ++s) off += (s < sg) ? segtot[s * 64 + c] : 0.f;
; #pragma unroll
;               for (int i = 0; i < 8; ++i) cumb[(8 * sg + i) * 64 + c] += off; }
;             __syncthreads();
;             {
;                 const f32x4_t c0 = *(const f32x4_t*)(cumb + j * 64 + c8), c1 = *(const f32x4_t*)(cumb + j * 64 + c8 + 4);
;                 float ah[8], bh[8], kh[8], rh[8];
; #pragma unroll
;                 for (int e = 0; e < 8; ++e) { const float cu = e < 4 ? c0[e & 3] : c1[e & 3]; const float Wt = __expf(cu), iW = __expf(-cu), Wm1 = __expf(cu - lw[e]);
;                     ah[e] = kk[e] * Wm1; bh[e] = -(kk[e] * av[e]) * iW; kh[e] = kd[e] * iW; rh[e] = rv[e] * Wt;
;                     if (j == 63) wc[c8 + e] = Wt; }
.LBB0_215:
	s_or_b64 exec, exec, s[12:13]
	v_mov_b32_e32 v59, 0
	v_mov_b32_e32 v60, 0
	s_and_saveexec_b64 s[12:13], s[46:47]
	ds_read_b32 v60, v114 offset:256
	s_or_b64 exec, exec, s[12:13]
	s_and_saveexec_b64 s[12:13], s[48:49]
	ds_read_b32 v59, v114 offset:512
	s_or_b64 exec, exec, s[12:13]
	v_mov_b32_e32 v61, 0
	v_mov_b32_e32 v62, 0
	s_and_saveexec_b64 s[12:13], s[50:51]
	ds_read_b32 v62, v114 offset:768
	s_or_b64 exec, exec, s[12:13]
	s_and_saveexec_b64 s[12:13], s[52:53]
	ds_read_b32 v61, v114 offset:1024
	s_or_b64 exec, exec, s[12:13]
	v_mov_b32_e32 v63, 0
	v_mov_b32_e32 v64, 0
	s_and_saveexec_b64 s[12:13], s[54:55]
	ds_read_b32 v64, v114 offset:1280
	s_or_b64 exec, exec, s[12:13]
	s_and_saveexec_b64 s[12:13], s[56:57]
	ds_read_b32 v63, v114 offset:1536
	s_or_b64 exec, exec, s[12:13]
	s_waitcnt lgkmcnt(0)
	v_add_f32_e32 v58, v58, v60
	v_add_f32_e32 v58, v58, v59
	v_add_f32_e32 v58, v58, v62
	v_add_f32_e32 v58, v58, v61
	v_add_f32_e32 v60, v58, v64
	ds_read2st64_b32 v[58:59], v159 offset1:1
	v_add_f32_e32 v177, v60, v63
	ds_read2st64_b32 v[60:61], v159 offset0:2 offset1:3
	ds_read2st64_b32 v[62:63], v159 offset0:4 offset1:5
	ds_read2st64_b32 v[64:65], v159 offset0:6 offset1:7
	s_waitcnt lgkmcnt(3)
	v_add_f32_e32 v58, v177, v58
	v_add_f32_e32 v59, v177, v59
	ds_write2st64_b32 v159, v58, v59 offset1:1
	s_waitcnt lgkmcnt(3)
	v_add_f32_e32 v58, v177, v60
	v_add_f32_e32 v59, v177, v61
	ds_write2st64_b32 v159, v58, v59 offset0:2 offset1:3
	s_waitcnt lgkmcnt(3)
	v_add_f32_e32 v58, v177, v62
	v_add_f32_e32 v59, v177, v63
	ds_write2st64_b32 v159, v58, v59 offset0:4 offset1:5
	s_waitcnt lgkmcnt(3)
	v_add_f32_e32 v58, v177, v64
	v_add_f32_e32 v59, v177, v65
	ds_write2st64_b32 v159, v58, v59 offset0:6 offset1:7
	s_waitcnt lgkmcnt(0)
	s_barrier
	ds_read_b128 v[58:61], v112
	ds_read_b128 v[62:65], v112 offset:16
	s_waitcnt lgkmcnt(1)
	v_mul_f32_e32 v177, 0x3fb8aa3b, v58
	v_exp_f32_e32 v177, v177
	s_and_saveexec_b64 s[12:13], s[42:43]
	ds_write_b32 v115, v177
	s_or_b64 exec, exec, s[12:13]
	v_mul_f32_e32 v178, 0x3fb8aa3b, v59
	v_exp_f32_e32 v178, v178
	s_and_saveexec_b64 s[12:13], s[42:43]
	ds_write_b32 v115, v178 offset:4
	s_or_b64 exec, exec, s[12:13]
	v_mul_f32_e32 v179, 0x3fb8aa3b, v60
	v_exp_f32_e32 v179, v179
	s_and_saveexec_b64 s[12:13], s[42:43]
	ds_write_b32 v115, v179 offset:8
	s_or_b64 exec, exec, s[12:13]
	v_mul_f32_e32 v180, 0x3fb8aa3b, v61
	v_exp_f32_e32 v180, v180
	s_and_saveexec_b64 s[12:13], s[42:43]
	ds_write_b32 v115, v180 offset:12
	s_or_b64 exec, exec, s[12:13]
	s_waitcnt lgkmcnt(0)
	v_mul_f32_e32 v181, 0x3fb8aa3b, v62
	v_exp_f32_e32 v181, v181
	s_and_saveexec_b64 s[12:13], s[42:43]
	ds_write_b32 v115, v181 offset:16
	s_or_b64 exec, exec, s[12:13]
	v_mul_f32_e32 v182, 0x3fb8aa3b, v63
	v_exp_f32_e32 v182, v182
	s_and_saveexec_b64 s[12:13], s[42:43]
	ds_write_b32 v115, v182 offset:20
	s_or_b64 exec, exec, s[12:13]
	v_mul_f32_e32 v183, 0x3fb8aa3b, v64
	v_exp_f32_e32 v183, v183
	s_and_saveexec_b64 s[12:13], s[42:43]
	ds_write_b32 v115, v183 offset:24
	s_or_b64 exec, exec, s[12:13]
	v_mul_f32_e32 v184, 0x3fb8aa3b, v65
	v_exp_f32_e32 v184, v184
	s_and_saveexec_b64 s[12:13], s[42:43]
	ds_write_b32 v115, v184 offset:28
	s_or_b64 exec, exec, s[12:13]
	v_add_f32_e32 v33, v33, v41
	v_mul_f32_e32 v33, 0xbfb8aa3b, v33
	v_add_f32_e32 v32, v32, v40
	v_exp_f32_e32 v33, v33
	v_mul_f32_e32 v32, 0xbfb8aa3b, v32
	v_exp_f32_e32 v32, v32
	v_add_f32_e32 v31, v31, v39
	v_add_f32_e32 v26, v26, v34
	v_add_f32_e32 v34, v146, v147
	v_mul_f32_e32 v31, 0xbfb8aa3b, v31
	v_add_f32_e32 v33, 1.0, v33
	v_max_f32_e32 v34, 0x179abe15, v34
	v_exp_f32_e32 v31, v31
	v_rcp_f32_e32 v33, v33
	v_sub_f32_e32 v39, v65, v57
	v_rsq_f32_e32 v34, v34
	v_add_f32_e32 v32, 1.0, v32
	v_mul_f32_e32 v39, 0x3fb8aa3b, v39
	v_add_f32_e32 v30, v30, v38
	v_rcp_f32_e32 v32, v32
	v_mul_f32_e32 v38, 0xbfb8aa3b, v65
	v_exp_f32_e32 v39, v39
	v_exp_f32_e32 v38, v38
	v_add_f32_e32 v28, v28, v36
	v_mul_f32_e32 v30, 0xbfb8aa3b, v30
	v_add_f32_e32 v31, 1.0, v31
	v_add_f32_e32 v36, -1.0, v33
	v_mul_f32_e32 v40, 0xbfb8aa3b, v64
	v_add_f32_e32 v29, v29, v37
	v_exp_f32_e32 v30, v30
	v_rcp_f32_e32 v31, v31
	v_fma_f32 v36, v36, v53, 1.0
	v_mul_f32_e32 v37, v176, v34
	v_exp_f32_e32 v40, v40
	v_mul_f32_e32 v36, v36, v175
	v_mul_f32_e32 v39, v37, v39
	v_mul_f32_e64 v33, v37, -v33
	v_add_f32_e32 v37, -1.0, v32
	v_mul_f32_e32 v29, 0xbfb8aa3b, v29
	v_mul_f32_e32 v33, v33, v38
	v_mul_f32_e32 v36, v36, v38
	v_fma_f32 v37, v37, v52, 1.0
	v_mul_f32_e32 v38, v174, v34
	v_sub_f32_e32 v41, v64, v56
	v_mul_f32_e32 v52, 0xbfb8aa3b, v63
	v_exp_f32_e32 v29, v29
	v_mul_f32_e32 v37, v37, v173
	v_mul_f32_e32 v41, 0x3fb8aa3b, v41
	v_mul_f32_e64 v32, v38, -v32
	v_exp_f32_e32 v52, v52
	v_sub_f32_e32 v53, v63, v55
	v_add_f32_e32 v30, 1.0, v30
	v_exp_f32_e32 v41, v41
	v_mul_f32_e32 v32, v32, v40
	v_mul_f32_e32 v37, v37, v40
	v_add_f32_e32 v40, -1.0, v31
	v_mul_f32_e32 v53, 0x3fb8aa3b, v53
	v_mul_f32_e32 v28, 0xbfb8aa3b, v28
	v_rcp_f32_e32 v30, v30
	v_fma_f32 v40, v40, v51, 1.0
	v_mul_f32_e32 v51, v172, v34
	v_exp_f32_e32 v53, v53
	v_exp_f32_e32 v28, v28
	v_mul_f32_e32 v40, v40, v171
	v_mul_f32_e64 v31, v51, -v31
	v_sub_f32_e32 v54, v62, v54
	v_add_f32_e32 v27, v27, v35
	v_add_f32_e32 v29, 1.0, v29
	v_and_b32_e32 v35, 0xffff0000, v25
	v_lshlrev_b32_e32 v25, 16, v25
	v_mul_f32_e32 v31, v31, v52
	v_mul_f32_e32 v40, v40, v52
	v_mul_f32_e32 v52, 0xbfb8aa3b, v62
	v_mul_f32_e32 v54, 0x3fb8aa3b, v54
	v_rcp_f32_e32 v29, v29
	v_mul_f32_e32 v41, v38, v41
	v_mul_f32_e32 v38, v183, v25
	v_and_b32_e32 v25, 0xffff0000, v24
	v_exp_f32_e32 v52, v52
	v_exp_f32_e32 v54, v54
	v_mul_f32_e32 v53, v51, v53
	v_mul_f32_e32 v51, v182, v25
; __device__ __forceinline__ unsigned pk2(float lo, float hi) { const f32x2_cv v = {lo, hi}; const bf16x2_cv b = __builtin_convertvector(v, bf16x2_cv); return __builtin_bit_cast(unsigned, b); }
; template <bool PA> ...
;     ...
;                 for (int e = 0; e < 8; ++e) { const float cu = e < 4 ? c0[e & 3] : c1[e & 3]; const float Wt = __expf(cu), iW = __expf(-cu), Wm1 = __expf(cu - lw[e]);
;                     ah[e] = kk[e] * Wm1; bh[e] = -(kk[e] * av[e]) * iW; kh[e] = kd[e] * iW; rh[e] = rv[e] * Wt;
;                     if (j == 63) wc[c8 + e] = Wt; }
;                 u32x4_t w;
;                 w.x = pk2(ah[0], ah[1]); w.y = pk2(ah[2], ah[3]); w.z = pk2(ah[4], ah[5]); w.w = pk2(ah[6], ah[7]); *(u32x4_t*)(MAT(0) + j * 72 + c8) = w;
;                 u32x4_t wb, wk;
;                 wb.x = pk2(bh[0], bh[1]); wb.y = pk2(bh[2], bh[3]); wb.z = pk2(bh[4], bh[5]); wb.w = pk2(bh[6], bh[7]); *(u32x4_t*)(MAT(1) + j * 72 + c8) = wb;
;                 wk.x = pk2(kh[0], kh[1]); wk.y = pk2(kh[2], kh[3]); wk.z = pk2(kh[4], kh[5]); wk.w = pk2(kh[6], kh[7]); *(u32x4_t*)(MAT(2) + j * 72 + c8) = wk;
;                 w.x = pk2(rh[0], rh[1]); w.y = pk2(rh[2], rh[3]); w.z = pk2(rh[4], rh[5]); w.w = pk2(rh[6], rh[7]); *(u32x4_t*)(MAT(3) + j * 72 + c8) = w;
;                 { const unsigned wba[4] = {wb.x, wb.y, wb.z, wb.w}, wka[4] = {wk.x, wk.y, wk.z, wk.w}, wva[4] = {vraw.x, vraw.y, vraw.z, vraw.w};
; #pragma unroll
;                   for (int q = 0; q < 4; ++q) { bf16* d4 = MAT(4) + (c8 + 2 * q) * 72 + j; bf16* d5 = MAT(5) + (c8 + 2 * q) * 72 + j; bf16* d6 = MAT(6) + (c8 + 2 * q) * 72 + j;
;                       d4[0] = (bf16)(wba[q] & 0xffffu); d4[72] = (bf16)(wba[q] >> 16); d5[0] = (bf16)(wka[q] & 0xffffu); d5[72] = (bf16)(wka[q] >> 16); d6[0] = (bf16)(wva[q] & 0xffffu); d6[72] = (bf16)(wva[q] >> 16); } }
;                 if (haveT) *(u32x4_t*)(MAT(9) + j * 72 + c8) = tld;
;                 st_rm(MAT(7), Sacc, mt, ntb, r16, kq);
;                 if (PA) st_rm(MAT(12), S2acc, mt, ntb, r16, kq);
	v_add_f32_e32 v25, -1.0, v30
	v_sub_f32_e32 v49, v61, v49
	v_add_f32_e32 v28, 1.0, v28
	v_fma_f32 v25, v25, v50, 1.0
	v_mul_f32_e32 v55, 0xbfb8aa3b, v61
	v_mul_f32_e32 v49, 0x3fb8aa3b, v49
	v_mul_f32_e32 v27, 0xbfb8aa3b, v27
	v_rcp_f32_e32 v28, v28
	v_mul_f32_e32 v25, v25, v169
	v_mul_f32_e32 v50, v170, v34
	v_exp_f32_e32 v55, v55
	v_exp_f32_e32 v49, v49
	v_exp_f32_e32 v27, v27
	v_mul_f32_e32 v54, v50, v54
	v_mul_f32_e64 v30, v50, -v30
	v_mul_f32_e32 v50, v25, v52
	v_add_f32_e32 v25, -1.0, v29
	v_lshlrev_b32_e32 v24, 16, v24
	v_fma_f32 v25, v25, v45, 1.0
	v_mul_f32_e32 v45, v168, v34
	v_mul_f32_e32 v30, v30, v52
	v_mul_f32_e32 v52, v181, v24
	v_and_b32_e32 v24, 0xffff0000, v23
	v_mul_f32_e32 v25, v25, v167
	v_mul_f32_e64 v29, v45, -v29
	v_sub_f32_e32 v48, v60, v48
	v_mul_f32_e32 v49, v45, v49
	v_mul_f32_e32 v29, v29, v55
	v_mul_f32_e32 v45, v25, v55
	v_mul_f32_e32 v55, v180, v24
	v_add_f32_e32 v24, -1.0, v28
	v_mul_f32_e32 v48, 0x3fb8aa3b, v48
	v_add_f32_e32 v27, 1.0, v27
	v_fma_f32 v24, v24, v44, 1.0
	v_mul_f32_e32 v44, 0xbfb8aa3b, v60
	v_exp_f32_e32 v48, v48
	v_rcp_f32_e32 v27, v27
	v_exp_f32_e32 v44, v44
	v_mul_f32_e32 v25, v166, v34
	v_mul_f32_e32 v24, v24, v165
	v_mul_f32_e32 v48, v25, v48
	v_mul_f32_e64 v25, v25, -v28
	v_sub_f32_e32 v47, v59, v47
	v_mul_f32_e32 v26, 0xbfb8aa3b, v26
	v_mul_f32_e32 v28, v25, v44
	v_mul_f32_e32 v44, v24, v44
	v_add_f32_e32 v24, -1.0, v27
	v_mul_f32_e32 v47, 0x3fb8aa3b, v47
	v_exp_f32_e32 v26, v26
	v_fma_f32 v24, v24, v43, 1.0
	v_mul_f32_e32 v43, 0xbfb8aa3b, v59
	v_exp_f32_e32 v47, v47
	v_exp_f32_e32 v43, v43
	v_mul_f32_e32 v25, v164, v34
	v_add_f32_e32 v26, 1.0, v26
	v_mul_f32_e32 v24, v24, v163
	v_mul_f32_e32 v47, v25, v47
	v_mul_f32_e64 v25, v25, -v27
	v_rcp_f32_e32 v26, v26
	v_mul_f32_e32 v27, v25, v43
	v_mul_f32_e32 v43, v24, v43
	v_mul_f32_e32 v24, v162, v34
	v_sub_f32_e32 v34, v58, v46
	v_mul_f32_e32 v34, 0x3fb8aa3b, v34
	v_lshlrev_b32_e32 v23, 16, v23
	v_mul_f32_e32 v25, 0xbfb8aa3b, v58
	v_exp_f32_e32 v34, v34
	v_mul_f32_e32 v56, v179, v23
	v_and_b32_e32 v23, 0xffff0000, v22
	v_exp_f32_e32 v25, v25
	v_mul_f32_e32 v57, v178, v23
	v_add_f32_e32 v23, -1.0, v26
	v_fma_f32 v23, v23, v42, 1.0
	v_lshlrev_b32_e32 v22, 16, v22
	v_mul_f32_e32 v23, v23, v161
	v_mul_f32_e32 v34, v24, v34
	v_mul_f32_e64 v24, v24, -v26
	v_mul_f32_e32 v35, v184, v35
	v_mul_f32_e32 v26, v24, v25
	v_mul_f32_e32 v42, v23, v25
	v_mul_f32_e32 v46, v177, v22
	v_cvt_pk_bf16_f32 v22, v34, v47
	v_cvt_pk_bf16_f32 v23, v48, v49
	v_cvt_pk_bf16_f32 v24, v54, v53
	v_cvt_pk_bf16_f32 v25, v41, v39
	ds_write_b128 v68, v[22:25]
	v_cvt_pk_bf16_f32 v22, v26, v27
	v_cvt_pk_bf16_f32 v23, v28, v29
	v_cvt_pk_bf16_f32 v24, v30, v31
	v_cvt_pk_bf16_f32 v25, v32, v33
	v_cvt_pk_bf16_f32 v26, v42, v43
	v_cvt_pk_bf16_f32 v27, v44, v45
	v_cvt_pk_bf16_f32 v28, v50, v40
	v_cvt_pk_bf16_f32 v29, v37, v36
	v_cvt_pk_bf16_f32 v30, v46, v57
	v_cvt_pk_bf16_f32 v31, v56, v55
	v_cvt_pk_bf16_f32 v32, v52, v51
	v_cvt_pk_bf16_f32 v33, v38, v35
	ds_write_b128 v68, v[22:25] offset:9216
	ds_write_b128 v68, v[26:29] offset:18432
	ds_write_b128 v68, v[30:33] offset:27648
	ds_write_b16 v154, v22 offset:36864
	ds_write_b16_d16_hi v154, v22 offset:37008
	ds_write_b16 v154, v26 offset:46080
	ds_write_b16_d16_hi v154, v26 offset:46224
	s_nop 0
	ds_write_b16 v154, v18 offset:55296
	ds_write_b16_d16_hi v154, v18 offset:55440
	ds_write_b16 v154, v23 offset:37152
	ds_write_b16_d16_hi v154, v23 offset:37296
	ds_write_b16 v154, v27 offset:46368
	ds_write_b16_d16_hi v154, v27 offset:46512
	ds_write_b16 v154, v19 offset:55584
	ds_write_b16_d16_hi v154, v19 offset:55728
	ds_write_b16 v185, v24 offset:37440
	ds_write_b16_d16_hi v185, v24 offset:37584
	ds_write_b16 v185, v28 offset:46656
	ds_write_b16_d16_hi v185, v28 offset:46800
	ds_write_b16 v185, v20 offset:55872
	ds_write_b16_d16_hi v185, v20 offset:56016
	ds_write_b16 v185, v25 offset:37728
	ds_write_b16_d16_hi v185, v25 offset:37872
	ds_write_b16 v185, v29 offset:46944
	ds_write_b16_d16_hi v185, v29 offset:47088
	ds_write_b16 v185, v21 offset:56160
	ds_write_b16_d16_hi v185, v21 offset:56304
	v_cvt_pk_bf16_f32 v18, v2, v3
	v_cvt_pk_bf16_f32 v19, v4, v5
	s_nop 1
	v_mov_b32_dpp v200, v18 quad_perm:[1,0,3,2] row_mask:0xf bank_mask:0xf
	v_add_u32_e32 v229, v194, v116
	v_perm_b32 v200, v200, v18, v195
	ds_write_b32 v229, v200 offset:64512
	s_nop 1
	v_mov_b32_dpp v228, v19 quad_perm:[1,0,3,2] row_mask:0xf bank_mask:0xf
	v_perm_b32 v228, v228, v19, v195
	ds_write_b32 v229, v228 offset:64800
	v_cvt_pk_bf16_f32 v18, v6, v7
	v_cvt_pk_bf16_f32 v0, v8, v0
	s_nop 1
	v_mov_b32_dpp v200, v18 quad_perm:[1,0,3,2] row_mask:0xf bank_mask:0xf
	v_perm_b32 v200, v200, v18, v195
	ds_write_b32 v229, v200 offset:64544
	s_nop 1
	v_mov_b32_dpp v228, v0 quad_perm:[1,0,3,2] row_mask:0xf bank_mask:0xf
	v_perm_b32 v228, v228, v0, v195
	ds_write_b32 v229, v228 offset:64832
	v_cvt_pk_bf16_f32 v0, v10, v11
	v_cvt_pk_bf16_f32 v18, v12, v13
	s_nop 1
	v_mov_b32_dpp v200, v0 quad_perm:[1,0,3,2] row_mask:0xf bank_mask:0xf
	v_add_u32_e32 v229, v194, v117
	v_perm_b32 v200, v200, v0, v195
	ds_write_b32 v229, v200
	s_nop 1
	v_mov_b32_dpp v228, v18 quad_perm:[1,0,3,2] row_mask:0xf bank_mask:0xf
	v_perm_b32 v228, v228, v18, v195
	ds_write_b32 v229, v228 offset:288
	v_cvt_pk_bf16_f32 v0, v14, v15
	v_cvt_pk_bf16_f32 v18, v16, v17
	s_nop 1
	v_mov_b32_dpp v200, v0 quad_perm:[1,0,3,2] row_mask:0xf bank_mask:0xf
	v_perm_b32 v200, v200, v0, v195
	ds_write_b32 v229, v200 offset:32
	s_nop 1
	v_mov_b32_dpp v228, v18 quad_perm:[1,0,3,2] row_mask:0xf bank_mask:0xf
	v_perm_b32 v228, v228, v18, v195
	ds_write_b32 v229, v228 offset:320
	s_waitcnt lgkmcnt(0)
	s_barrier
; template <bool PA> ...
;     ...
;             f32x4_t Pacc[2], Tacc[2], Xacc[2], Yacc[2], tmp[2];
;             const f32x4_t z4 = (f32x4_t){0.f, 0.f, 0.f, 0.f};
;             Tacc[0] = z4; Tacc[1] = z4;
;             if (!haveT) {
;             Pacc[0] = z4; Pacc[1] = z4; mm2(Pacc, MAT(0), MAT(1), mt, ntb, r16, kq);
; #pragma unroll
;             for (int i = 0; i < 2; ++i)
; #pragma unroll
;                 for (int e = 0; e < 4; ++e) { const int t = 16 * mt + 4 * kq + e, s = 16 * (ntb + i) + r16; Pacc[i][e] = (s < t) ? Pacc[i][e] : 0.f; Tacc[i][e] = Pacc[i][e] + ((s == t) ? 1.f : 0.f); }
;             st_rm(MAT(8), Pacc, mt, ntb, r16, kq); st_tr(MAT(9), Pacc, mt, ntb, r16, kq);
;             }
;             tmp[0] = z4; tmp[1] = z4; mm2(tmp, MAT(0), MAT(2), mt, ntb, r16, kq);
; #pragma unroll
;             for (int i = 0; i < 2; ++i)
; #pragma unroll
;                 for (int e = 0; e < 4; ++e) { const int t = 16 * mt + 4 * kq + e, s = 16 * (ntb + i) + r16; tmp[i][e] = (s < t) ? tmp[i][e] : 0.f; }
;             st_rm(MAT(10), tmp, mt, ntb, r16, kq);
;             f32x4_t X2acc[2]; X2acc[0] = z4; X2acc[1] = z4;
;             if (PA) mm2(X2acc, MAT(0), MAT(12), mt, ntb, r16, kq);
;             if (!PA) {
;             tmp[0] = z4; tmp[1] = z4; mm2(tmp, MAT(3), MAT(1), mt, ntb, r16, kq);
; #pragma unroll
;             for (int i = 0; i < 2; ++i)
; #pragma unroll
;                 for (int e = 0; e < 4; ++e) { const int t = 16 * mt + 4 * kq + e, s = 16 * (ntb + i) + r16; tmp[i][e] = (s <= t) ? tmp[i][e] : 0.f; }
;             st_rm(MAT(11), tmp, mt, ntb, r16, kq);
;             tmp[0] = z4; tmp[1] = z4; mm2(tmp, MAT(3), MAT(2), mt, ntb, r16, kq);
; #pragma unroll
;             for (int i = 0; i < 2; ++i)
; #pragma unroll
;                 for (int e = 0; e < 4; ++e) { const int t = 16 * mt + 4 * kq + e, s = 16 * (ntb + i) + r16; tmp[i][e] = (s <= t) ? tmp[i][e] : 0.f; }
;             st_rm(MAT(12), tmp, mt, ntb, r16, kq);
;             }
;             Xacc[0] = z4; Xacc[1] = z4; mm2(Xacc, MAT(0), MAT(7), mt, ntb, r16, kq);
;             Yacc[0] = z4; Yacc[1] = z4; if (!PA) mm2(Yacc, MAT(3), MAT(7), mt, ntb, r16, kq);
;             __syncthreads();
;             if (!haveT) {
;             tmp[0] = z4; tmp[1] = z4; mm2(tmp, MAT(8), MAT(9), mt, ntb, r16, kq);
	ds_read_b128 v[186:189], v69
	ds_read_b128 v[190:193], v118 offset:9216
	ds_read_b128 v[204:207], v118 offset:11520
	ds_read_b128 v[208:211], v69 offset:64
	ds_read_b128 v[212:215], v118 offset:9280
	ds_read_b128 v[216:219], v118 offset:11584
	ds_read_b128 v[220:223], v69
	ds_read_b128 v[224:227], v118 offset:18432
	s_nop 0
	s_nop 0
	s_nop 0
	s_waitcnt lgkmcnt(6)
	v_mfma_f32_16x16x32_bf16 v[22:25], v[186:189], v[190:193], 0
	ds_read_b128 v[190:193], v118 offset:20736
	s_waitcnt lgkmcnt(6)
	v_mfma_f32_16x16x32_bf16 v[18:21], v[186:189], v[204:207], 0
	ds_read_b128 v[186:189], v69 offset:64
	ds_read_b128 v[204:207], v118 offset:18496
	s_nop 0
	s_nop 0
	s_waitcnt lgkmcnt(6)
	v_mfma_f32_16x16x32_bf16 v[22:25], v[208:211], v[212:215], v[22:25]
	ds_read_b128 v[212:215], v118 offset:20800
	s_nop 0
	s_waitcnt lgkmcnt(6)
	v_mfma_f32_16x16x32_bf16 v[18:21], v[208:211], v[216:219], v[18:21]
	s_nop 4
	v_cndmask_b32_e64 v0, 0, v22, s[58:59]
	v_cndmask_b32_e64 v22, v23, 0, s[60:61]
	v_cndmask_b32_e64 v23, 0, v24, s[62:63]
	v_cndmask_b32_e64 v24, 0, v25, s[64:65]
	v_cndmask_b32_e64 v25, 0, v18, s[66:67]
	v_cndmask_b32_e64 v26, v19, 0, s[68:69]
	v_cndmask_b32_e64 v27, 0, v20, s[70:71]
	v_cndmask_b32_e64 v21, 0, v21, s[72:73]
	v_add_f32_e32 v65, v143, v21
	v_cvt_pk_bf16_f32 v18, v0, v22
	v_cvt_pk_bf16_f32 v20, v25, v26
	v_cvt_pk_bf16_f32 v21, v27, v21
	v_cvt_pk_bf16_f32 v19, v23, v24
	s_nop 1
	v_mov_b32_dpp v200, v18 quad_perm:[1,0,3,2] row_mask:0xf bank_mask:0xf
	v_add_u32_e32 v229, v194, v119
	v_perm_b32 v200, v200, v18, v195
	ds_write_b32 v229, v200
	s_nop 1
	v_mov_b32_dpp v228, v19 quad_perm:[1,0,3,2] row_mask:0xf bank_mask:0xf
	v_perm_b32 v228, v228, v19, v195
	ds_write_b32 v229, v228 offset:288
	s_nop 1
	v_mov_b32_dpp v200, v20 quad_perm:[1,0,3,2] row_mask:0xf bank_mask:0xf
	v_perm_b32 v200, v200, v20, v195
	ds_write_b32 v229, v200 offset:32
	s_nop 1
	v_mov_b32_dpp v228, v21 quad_perm:[1,0,3,2] row_mask:0xf bank_mask:0xf
	v_perm_b32 v228, v228, v21, v195
	ds_write_b32 v229, v228 offset:320
	ds_write_b64 v120, v[18:19]
	ds_write_b64 v120, v[20:21] offset:2304
	v_add_f32_e32 v59, v137, v22
	v_add_f32_e32 v60, v138, v23
	v_add_f32_e32 v61, v139, v24
	v_add_f32_e32 v62, v140, v25
	v_add_f32_e32 v63, v141, v26
	v_add_f32_e32 v64, v142, v27
	s_nop 0
	s_nop 0
	s_nop 0
	s_waitcnt lgkmcnt(0)
	v_mfma_f32_16x16x32_bf16 v[22:25], v[220:223], v[224:227], 0
	v_add_f32_e32 v58, v136, v0
	s_waitcnt lgkmcnt(0)
	v_mfma_f32_16x16x32_bf16 v[18:21], v[220:223], v[190:193], 0
	s_nop 0
	s_nop 0
	s_waitcnt lgkmcnt(0)
	v_mfma_f32_16x16x32_bf16 v[22:25], v[186:189], v[204:207], v[22:25]
	s_nop 0
	s_waitcnt lgkmcnt(0)
	v_mfma_f32_16x16x32_bf16 v[18:21], v[186:189], v[212:215], v[18:21]
	s_nop 4
	v_cndmask_b32_e64 v0, 0, v22, s[58:59]
	v_cndmask_b32_e64 v22, v23, 0, s[60:61]
	v_cndmask_b32_e64 v23, 0, v24, s[62:63]
	v_cndmask_b32_e64 v24, 0, v25, s[64:65]
	v_cndmask_b32_e64 v18, 0, v18, s[66:67]
	v_cndmask_b32_e64 v19, v19, 0, s[68:69]
	v_cvt_pk_bf16_f32 v0, v0, v22
	v_cndmask_b32_e64 v20, 0, v20, s[70:71]
	v_cndmask_b32_e64 v21, 0, v21, s[72:73]
	v_cvt_pk_bf16_f32 v22, v23, v24
	s_nop 1
	v_mov_b32_dpp v200, v0 quad_perm:[1,0,3,2] row_mask:0xf bank_mask:0xf
	v_add_u32_e32 v229, v194, v121
	v_perm_b32 v200, v200, v0, v195
	ds_write_b32 v229, v200
	s_nop 1
	v_mov_b32_dpp v228, v22 quad_perm:[1,0,3,2] row_mask:0xf bank_mask:0xf
	v_perm_b32 v228, v228, v22, v195
	ds_write_b32 v229, v228 offset:288
	v_cvt_pk_bf16_f32 v0, v18, v19
	v_cvt_pk_bf16_f32 v18, v20, v21
	s_nop 1
	v_mov_b32_dpp v200, v0 quad_perm:[1,0,3,2] row_mask:0xf bank_mask:0xf
	v_perm_b32 v200, v200, v0, v195
	ds_write_b32 v229, v200 offset:32
	s_nop 1
	v_mov_b32_dpp v228, v18 quad_perm:[1,0,3,2] row_mask:0xf bank_mask:0xf
	v_perm_b32 v228, v228, v18, v195
	ds_write_b32 v229, v228 offset:320
	ds_read_b128 v[22:25], v69
	ds_read_b128 v[42:45], v122
	ds_read_b128 v[46:49], v122 offset:2304
	ds_read_b128 v[18:21], v69 offset:64
	ds_read_b128 v[54:57], v122 offset:64
	ds_read_b128 v[50:53], v122 offset:2368
	ds_read_b128 v[38:41], v118 offset:64512
	ds_read_b128 v[34:37], v123
	ds_read_b128 v[30:33], v118 offset:64576
	ds_read_b128 v[26:29], v124
	s_waitcnt lgkmcnt(0)
	s_barrier
	ds_read_b128 v[186:189], v125
	ds_read_b128 v[190:193], v126
	ds_read_b128 v[204:207], v126 offset:2304
	ds_read_b128 v[208:211], v125 offset:64
	ds_read_b128 v[212:215], v126 offset:64
	ds_read_b128 v[216:219], v126 offset:2368
	s_nop 0
	s_nop 0
	s_nop 0
	s_waitcnt lgkmcnt(4)
	v_mfma_f32_16x16x32_bf16 v[166:169], v[186:189], v[190:193], 0
	v_cvt_pk_bf16_f32 v0, v58, v59
	s_waitcnt lgkmcnt(3)
	v_mfma_f32_16x16x32_bf16 v[162:165], v[186:189], v[204:207], 0
	s_nop 0
	s_nop 0
	s_waitcnt lgkmcnt(1)
	v_mfma_f32_16x16x32_bf16 v[166:169], v[208:211], v[212:215], v[166:169]
	s_nop 0
	s_waitcnt lgkmcnt(0)
	v_mfma_f32_16x16x32_bf16 v[162:165], v[208:211], v[216:219], v[162:165]
	s_nop 4
	v_cvt_pk_bf16_f32 v146, v166, v167
	v_cvt_pk_bf16_f32 v147, v168, v169
	s_nop 1
	v_mov_b32_dpp v200, v146 quad_perm:[1,0,3,2] row_mask:0xf bank_mask:0xf
	v_add_u32_e32 v229, v194, v116
	v_perm_b32 v200, v200, v146, v195
	ds_write_b32 v229, v200
	s_nop 1
	v_mov_b32_dpp v228, v147 quad_perm:[1,0,3,2] row_mask:0xf bank_mask:0xf
	v_perm_b32 v228, v228, v147, v195
	ds_write_b32 v229, v228 offset:288
	v_cvt_pk_bf16_f32 v162, v162, v163
	v_cvt_pk_bf16_f32 v163, v164, v165
	s_nop 1
	v_mov_b32_dpp v200, v162 quad_perm:[1,0,3,2] row_mask:0xf bank_mask:0xf
	v_perm_b32 v200, v200, v162, v195
	ds_write_b32 v229, v200 offset:32
	s_nop 1
	v_mov_b32_dpp v228, v163 quad_perm:[1,0,3,2] row_mask:0xf bank_mask:0xf
	v_perm_b32 v228, v228, v163, v195
	ds_write_b32 v229, v228 offset:320
	ds_write_b64 v127, v[146:147] offset:9216
	ds_write_b64 v127, v[162:163] offset:11520
	v_cvt_pk_bf16_f32 v146, v60, v61
	s_nop 1
	v_mov_b32_dpp v200, v0 quad_perm:[1,0,3,2] row_mask:0xf bank_mask:0xf
	v_perm_b32 v200, v200, v0, v195
	ds_write_b32 v229, v200 offset:18432
	s_nop 1
	v_mov_b32_dpp v228, v146 quad_perm:[1,0,3,2] row_mask:0xf bank_mask:0xf
	v_perm_b32 v228, v228, v146, v195
	ds_write_b32 v229, v228 offset:18720
	v_cvt_pk_bf16_f32 v0, v62, v63
	v_cvt_pk_bf16_f32 v146, v64, v65
	s_nop 1
	v_mov_b32_dpp v200, v0 quad_perm:[1,0,3,2] row_mask:0xf bank_mask:0xf
	v_perm_b32 v200, v200, v0, v195
	ds_write_b32 v229, v200 offset:18464
	s_nop 1
	v_mov_b32_dpp v228, v146 quad_perm:[1,0,3,2] row_mask:0xf bank_mask:0xf
	v_perm_b32 v228, v228, v146, v195
	ds_write_b32 v229, v228 offset:18752
	s_waitcnt lgkmcnt(0)
	s_barrier
; template <bool PA> ...
;     ...
;             for (int i = 1; i <= 5; ++i) {
;                 bf16* Pc = (i & 1) ? MAT(0) : MAT(8); bf16* PcT = (i & 1) ? MAT(1) : MAT(9); bf16* Pn = (i & 1) ? MAT(8) : MAT(0); bf16* PnT = (i & 1) ? MAT(9) : MAT(1);
;                 bf16* Tc = (i & 1) ? MAT(2) : MAT(3); bf16* Tn = (i & 1) ? MAT(3) : MAT(2);
;                 mm2(Tacc, Tc, PcT, mt, ntb, r16, kq);
;                 if (i < 5) { tmp[0] = z4; tmp[1] = z4; mm2(tmp, Pc, PcT, mt, ntb, r16, kq); st_rm(Pn, tmp, mt, ntb, r16, kq); st_tr(PnT, tmp, mt, ntb, r16, kq); }
;                 st_rm(Tn, Tacc, mt, ntb, r16, kq);
;                 __syncthreads();
;             }
	ds_read_b128 v[186:189], v69 offset:18432
	ds_read_b128 v[190:193], v118 offset:9216
	ds_read_b128 v[204:207], v118 offset:11520
	ds_read_b128 v[208:211], v69 offset:18496
	ds_read_b128 v[212:215], v118 offset:9280
	ds_read_b128 v[216:219], v118 offset:11584
	ds_read_b128 v[220:223], v69
	ds_read_b128 v[224:227], v69 offset:64
	s_nop 0
	s_nop 0
	s_nop 0
	s_waitcnt lgkmcnt(6)
	v_mfma_f32_16x16x32_bf16 v[58:61], v[186:189], v[190:193], v[58:61]
	s_waitcnt lgkmcnt(5)
	v_mfma_f32_16x16x32_bf16 v[62:65], v[186:189], v[204:207], v[62:65]
	s_nop 0
	s_nop 0
	s_nop 0
	s_waitcnt lgkmcnt(3)
	v_mfma_f32_16x16x32_bf16 v[58:61], v[208:211], v[212:215], v[58:61]
	s_waitcnt lgkmcnt(2)
	v_mfma_f32_16x16x32_bf16 v[62:65], v[208:211], v[216:219], v[62:65]
	s_nop 0
	s_nop 4
	v_cvt_pk_bf16_f32 v0, v58, v59
	s_waitcnt lgkmcnt(1)
	v_mfma_f32_16x16x32_bf16 v[166:169], v[220:223], v[190:193], 0
	v_mfma_f32_16x16x32_bf16 v[162:165], v[220:223], v[204:207], 0
	s_nop 0
	s_waitcnt lgkmcnt(0)
	v_mfma_f32_16x16x32_bf16 v[166:169], v[224:227], v[212:215], v[166:169]
	s_nop 7
	v_cvt_pk_bf16_f32 v146, v166, v167
	v_mfma_f32_16x16x32_bf16 v[162:165], v[224:227], v[216:219], v[162:165]
	v_cvt_pk_bf16_f32 v147, v168, v169
	s_nop 1
	v_mov_b32_dpp v200, v146 quad_perm:[1,0,3,2] row_mask:0xf bank_mask:0xf
	v_add_u32_e32 v229, v194, v155
	v_perm_b32 v200, v200, v146, v195
	ds_write_b32 v229, v200
	s_nop 1
	v_mov_b32_dpp v228, v147 quad_perm:[1,0,3,2] row_mask:0xf bank_mask:0xf
	v_perm_b32 v228, v228, v147, v195
	ds_write_b32 v229, v228 offset:288
	s_nop 2
	v_cvt_pk_bf16_f32 v162, v162, v163
	v_cvt_pk_bf16_f32 v163, v164, v165
	s_nop 1
	v_mov_b32_dpp v200, v162 quad_perm:[1,0,3,2] row_mask:0xf bank_mask:0xf
	v_perm_b32 v200, v200, v162, v195
	ds_write_b32 v229, v200 offset:32
	s_nop 1
	v_mov_b32_dpp v228, v163 quad_perm:[1,0,3,2] row_mask:0xf bank_mask:0xf
	v_perm_b32 v228, v228, v163, v195
	ds_write_b32 v229, v228 offset:320
	ds_write_b64 v120, v[146:147]
	ds_write_b64 v120, v[162:163] offset:2304
	v_cvt_pk_bf16_f32 v146, v60, v61
	s_nop 1
	v_mov_b32_dpp v200, v0 quad_perm:[1,0,3,2] row_mask:0xf bank_mask:0xf
	v_add_u32_e32 v229, v194, v156
	v_perm_b32 v200, v200, v0, v195
	ds_write_b32 v229, v200 offset:27648
	s_nop 1
	v_mov_b32_dpp v228, v146 quad_perm:[1,0,3,2] row_mask:0xf bank_mask:0xf
	v_perm_b32 v228, v228, v146, v195
	ds_write_b32 v229, v228 offset:27936
	v_cvt_pk_bf16_f32 v0, v62, v63
	v_cvt_pk_bf16_f32 v146, v64, v65
	s_nop 1
	v_mov_b32_dpp v200, v0 quad_perm:[1,0,3,2] row_mask:0xf bank_mask:0xf
	v_perm_b32 v200, v200, v0, v195
	ds_write_b32 v229, v200 offset:27680
	s_nop 1
	v_mov_b32_dpp v228, v146 quad_perm:[1,0,3,2] row_mask:0xf bank_mask:0xf
	v_perm_b32 v228, v228, v146, v195
	ds_write_b32 v229, v228 offset:27968
	s_waitcnt lgkmcnt(0)
	s_barrier
	ds_read_b128 v[186:189], v69 offset:27648
	ds_read_b128 v[190:193], v126
	ds_read_b128 v[204:207], v126 offset:2304
	ds_read_b128 v[208:211], v69 offset:27712
	ds_read_b128 v[212:215], v126 offset:64
	ds_read_b128 v[216:219], v126 offset:2368
	ds_read_b128 v[220:223], v125
	ds_read_b128 v[224:227], v125 offset:64
	s_nop 0
	s_nop 0
	s_nop 0
	s_waitcnt lgkmcnt(6)
	v_mfma_f32_16x16x32_bf16 v[58:61], v[186:189], v[190:193], v[58:61]
	s_waitcnt lgkmcnt(5)
	v_mfma_f32_16x16x32_bf16 v[62:65], v[186:189], v[204:207], v[62:65]
	s_nop 0
	s_nop 0
	s_nop 0
	s_waitcnt lgkmcnt(3)
	v_mfma_f32_16x16x32_bf16 v[58:61], v[208:211], v[212:215], v[58:61]
	s_waitcnt lgkmcnt(2)
	v_mfma_f32_16x16x32_bf16 v[62:65], v[208:211], v[216:219], v[62:65]
	s_nop 0
	s_nop 4
	v_cvt_pk_bf16_f32 v0, v58, v59
	s_waitcnt lgkmcnt(1)
	v_mfma_f32_16x16x32_bf16 v[166:169], v[220:223], v[190:193], 0
	v_mfma_f32_16x16x32_bf16 v[162:165], v[220:223], v[204:207], 0
	s_nop 0
	s_waitcnt lgkmcnt(0)
	v_mfma_f32_16x16x32_bf16 v[166:169], v[224:227], v[212:215], v[166:169]
	s_nop 7
	v_cvt_pk_bf16_f32 v146, v166, v167
	v_mfma_f32_16x16x32_bf16 v[162:165], v[224:227], v[216:219], v[162:165]
	v_cvt_pk_bf16_f32 v147, v168, v169
	s_nop 1
	v_mov_b32_dpp v200, v146 quad_perm:[1,0,3,2] row_mask:0xf bank_mask:0xf
	v_perm_b32 v200, v200, v146, v195
	ds_write_b32 v229, v200
	s_nop 1
	v_mov_b32_dpp v228, v147 quad_perm:[1,0,3,2] row_mask:0xf bank_mask:0xf
	v_perm_b32 v228, v228, v147, v195
	ds_write_b32 v229, v228 offset:288
	s_nop 2
	v_cvt_pk_bf16_f32 v162, v162, v163
	v_cvt_pk_bf16_f32 v163, v164, v165
	s_nop 1
	v_mov_b32_dpp v200, v162 quad_perm:[1,0,3,2] row_mask:0xf bank_mask:0xf
	v_perm_b32 v200, v200, v162, v195
	ds_write_b32 v229, v200 offset:32
	s_nop 1
	v_mov_b32_dpp v228, v163 quad_perm:[1,0,3,2] row_mask:0xf bank_mask:0xf
	v_perm_b32 v228, v228, v163, v195
	ds_write_b32 v229, v228 offset:320
	ds_write_b64 v127, v[146:147] offset:9216
	ds_write_b64 v127, v[162:163] offset:11520
	v_cvt_pk_bf16_f32 v146, v60, v61
	s_nop 1
	v_mov_b32_dpp v200, v0 quad_perm:[1,0,3,2] row_mask:0xf bank_mask:0xf
	v_perm_b32 v200, v200, v0, v195
	ds_write_b32 v229, v200 offset:18432
	s_nop 1
	v_mov_b32_dpp v228, v146 quad_perm:[1,0,3,2] row_mask:0xf bank_mask:0xf
	v_perm_b32 v228, v228, v146, v195
	ds_write_b32 v229, v228 offset:18720
	v_cvt_pk_bf16_f32 v0, v62, v63
	v_cvt_pk_bf16_f32 v146, v64, v65
	s_nop 1
	v_mov_b32_dpp v200, v0 quad_perm:[1,0,3,2] row_mask:0xf bank_mask:0xf
	v_perm_b32 v200, v200, v0, v195
	ds_write_b32 v229, v200 offset:18464
	s_nop 1
	v_mov_b32_dpp v228, v146 quad_perm:[1,0,3,2] row_mask:0xf bank_mask:0xf
	v_perm_b32 v228, v228, v146, v195
	ds_write_b32 v229, v228 offset:18752
	s_waitcnt lgkmcnt(0)
	s_barrier
; template <bool PA> ...
;     ...
;             for (int i = 1; i <= 5; ++i) {
;                 bf16* Pc = (i & 1) ? MAT(0) : MAT(8); bf16* PcT = (i & 1) ? MAT(1) : MAT(9); bf16* Pn = (i & 1) ? MAT(8) : MAT(0); bf16* PnT = (i & 1) ? MAT(9) : MAT(1);
;                 bf16* Tc = (i & 1) ? MAT(2) : MAT(3); bf16* Tn = (i & 1) ? MAT(3) : MAT(2);
;                 mm2(Tacc, Tc, PcT, mt, ntb, r16, kq);
;                 if (i < 5) { tmp[0] = z4; tmp[1] = z4; mm2(tmp, Pc, PcT, mt, ntb, r16, kq); st_rm(Pn, tmp, mt, ntb, r16, kq); st_tr(PnT, tmp, mt, ntb, r16, kq); }
;                 st_rm(Tn, Tacc, mt, ntb, r16, kq);
;                 __syncthreads();
;             }
	ds_read_b128 v[186:189], v69 offset:18432
	ds_read_b128 v[190:193], v118 offset:9216
	ds_read_b128 v[204:207], v118 offset:11520
	ds_read_b128 v[208:211], v69 offset:18496
	ds_read_b128 v[212:215], v118 offset:9280
	ds_read_b128 v[216:219], v118 offset:11584
	ds_read_b128 v[220:223], v69
	ds_read_b128 v[224:227], v69 offset:64
	s_nop 0
	s_nop 0
	s_nop 0
	s_waitcnt lgkmcnt(6)
	v_mfma_f32_16x16x32_bf16 v[58:61], v[186:189], v[190:193], v[58:61]
	s_waitcnt lgkmcnt(5)
	v_mfma_f32_16x16x32_bf16 v[62:65], v[186:189], v[204:207], v[62:65]
	s_nop 0
	s_nop 0
	s_nop 0
	s_waitcnt lgkmcnt(3)
	v_mfma_f32_16x16x32_bf16 v[58:61], v[208:211], v[212:215], v[58:61]
	s_waitcnt lgkmcnt(2)
	v_mfma_f32_16x16x32_bf16 v[62:65], v[208:211], v[216:219], v[62:65]
	s_nop 0
	s_nop 4
	v_cvt_pk_bf16_f32 v0, v58, v59
	s_waitcnt lgkmcnt(1)
	v_mfma_f32_16x16x32_bf16 v[166:169], v[220:223], v[190:193], 0
	v_mfma_f32_16x16x32_bf16 v[162:165], v[220:223], v[204:207], 0
	s_nop 0
	s_waitcnt lgkmcnt(0)
	v_mfma_f32_16x16x32_bf16 v[166:169], v[224:227], v[212:215], v[166:169]
	s_nop 7
	v_cvt_pk_bf16_f32 v146, v166, v167
	v_mfma_f32_16x16x32_bf16 v[162:165], v[224:227], v[216:219], v[162:165]
	v_cvt_pk_bf16_f32 v147, v168, v169
	s_nop 1
	v_mov_b32_dpp v200, v146 quad_perm:[1,0,3,2] row_mask:0xf bank_mask:0xf
	v_add_u32_e32 v229, v194, v155
	v_perm_b32 v200, v200, v146, v195
	ds_write_b32 v229, v200
	s_nop 1
	v_mov_b32_dpp v228, v147 quad_perm:[1,0,3,2] row_mask:0xf bank_mask:0xf
	v_perm_b32 v228, v228, v147, v195
	ds_write_b32 v229, v228 offset:288
	s_nop 2
	v_cvt_pk_bf16_f32 v162, v162, v163
	v_cvt_pk_bf16_f32 v163, v164, v165
	s_nop 1
	v_mov_b32_dpp v200, v162 quad_perm:[1,0,3,2] row_mask:0xf bank_mask:0xf
	v_perm_b32 v200, v200, v162, v195
	ds_write_b32 v229, v200 offset:32
	s_nop 1
	v_mov_b32_dpp v228, v163 quad_perm:[1,0,3,2] row_mask:0xf bank_mask:0xf
	v_perm_b32 v228, v228, v163, v195
	ds_write_b32 v229, v228 offset:320
	ds_write_b64 v120, v[146:147]
	ds_write_b64 v120, v[162:163] offset:2304
	v_cvt_pk_bf16_f32 v146, v60, v61
	s_nop 1
	v_mov_b32_dpp v200, v0 quad_perm:[1,0,3,2] row_mask:0xf bank_mask:0xf
	v_add_u32_e32 v229, v194, v156
	v_perm_b32 v200, v200, v0, v195
	ds_write_b32 v229, v200 offset:27648
	s_nop 1
	v_mov_b32_dpp v228, v146 quad_perm:[1,0,3,2] row_mask:0xf bank_mask:0xf
	v_perm_b32 v228, v228, v146, v195
	ds_write_b32 v229, v228 offset:27936
	v_cvt_pk_bf16_f32 v0, v62, v63
	v_cvt_pk_bf16_f32 v146, v64, v65
	s_nop 1
	v_mov_b32_dpp v200, v0 quad_perm:[1,0,3,2] row_mask:0xf bank_mask:0xf
	v_perm_b32 v200, v200, v0, v195
	ds_write_b32 v229, v200 offset:27680
	s_nop 1
	v_mov_b32_dpp v228, v146 quad_perm:[1,0,3,2] row_mask:0xf bank_mask:0xf
	v_perm_b32 v228, v228, v146, v195
	ds_write_b32 v229, v228 offset:27968
	s_waitcnt lgkmcnt(0)
	s_barrier
; template <bool PA> ...
;     ...
;             for (int i = 1; i <= 5; ++i) {
;                 bf16* Pc = (i & 1) ? MAT(0) : MAT(8); bf16* PcT = (i & 1) ? MAT(1) : MAT(9); bf16* Pn = (i & 1) ? MAT(8) : MAT(0); bf16* PnT = (i & 1) ? MAT(9) : MAT(1);
;                 bf16* Tc = (i & 1) ? MAT(2) : MAT(3); bf16* Tn = (i & 1) ? MAT(3) : MAT(2);
;                 mm2(Tacc, Tc, PcT, mt, ntb, r16, kq);
;                 if (i < 5) { tmp[0] = z4; tmp[1] = z4; mm2(tmp, Pc, PcT, mt, ntb, r16, kq); st_rm(Pn, tmp, mt, ntb, r16, kq); st_tr(PnT, tmp, mt, ntb, r16, kq); }
;                 st_rm(Tn, Tacc, mt, ntb, r16, kq);
;                 __syncthreads();
;             }
;             }
;             if (PA && tlow) *(u32x4_t*)(tbuf + ((size_t)strm * NCHA + p) * 2304 + tunit * 8) = *(const u32x4_t*)(MAT(3) + j * 72 + c8);
;             const bf16* Tm = haveT ? MAT(9) : MAT(3);
;             mm2(Xacc, MAT(10), MAT(6), mt, ntb, r16, kq);
	ds_read_b128 v[186:189], v69 offset:27648
	ds_read_b128 v[190:193], v126
	ds_read_b128 v[204:207], v126 offset:2304
	ds_read_b128 v[208:211], v69 offset:27712
	ds_read_b128 v[212:215], v126 offset:64
	ds_read_b128 v[216:219], v126 offset:2368
	ds_read_b128 v[220:223], v125
	ds_read_b128 v[224:227], v125 offset:64
	s_nop 0
	s_nop 0
	s_nop 0
	s_waitcnt lgkmcnt(6)
	v_mfma_f32_16x16x32_bf16 v[58:61], v[186:189], v[190:193], v[58:61]
	s_waitcnt lgkmcnt(5)
	v_mfma_f32_16x16x32_bf16 v[62:65], v[186:189], v[204:207], v[62:65]
	s_nop 0
	s_nop 0
	s_nop 0
	s_waitcnt lgkmcnt(3)
	v_mfma_f32_16x16x32_bf16 v[58:61], v[208:211], v[212:215], v[58:61]
	s_waitcnt lgkmcnt(2)
	v_mfma_f32_16x16x32_bf16 v[62:65], v[208:211], v[216:219], v[62:65]
	s_nop 0
	s_nop 4
	v_cvt_pk_bf16_f32 v0, v58, v59
	s_waitcnt lgkmcnt(1)
	v_mfma_f32_16x16x32_bf16 v[166:169], v[220:223], v[190:193], 0
	v_mfma_f32_16x16x32_bf16 v[162:165], v[220:223], v[204:207], 0
	s_nop 0
	s_waitcnt lgkmcnt(0)
	v_mfma_f32_16x16x32_bf16 v[166:169], v[224:227], v[212:215], v[166:169]
	v_mov_b32_e32 v174, v212
	v_mov_b32_e32 v175, v213
	v_mov_b32_e32 v176, v214
	v_mov_b32_e32 v177, v215
	s_nop 7
	v_cvt_pk_bf16_f32 v146, v166, v167
	v_mfma_f32_16x16x32_bf16 v[162:165], v[224:227], v[216:219], v[162:165]
	v_mov_b32_e32 v178, v216
	v_mov_b32_e32 v179, v217
	v_mov_b32_e32 v180, v218
	v_mov_b32_e32 v181, v219
	v_mov_b32_e32 v170, v224
	v_mov_b32_e32 v171, v225
	v_mov_b32_e32 v172, v226
	v_mov_b32_e32 v173, v227
	v_cvt_pk_bf16_f32 v147, v168, v169
	s_nop 1
	v_mov_b32_dpp v200, v146 quad_perm:[1,0,3,2] row_mask:0xf bank_mask:0xf
	v_perm_b32 v200, v200, v146, v195
	ds_write_b32 v229, v200
	s_nop 1
	v_mov_b32_dpp v228, v147 quad_perm:[1,0,3,2] row_mask:0xf bank_mask:0xf
	v_perm_b32 v228, v228, v147, v195
	ds_write_b32 v229, v228 offset:288
	s_nop 2
	v_cvt_pk_bf16_f32 v162, v162, v163
	v_cvt_pk_bf16_f32 v163, v164, v165
	s_nop 1
	v_mov_b32_dpp v200, v162 quad_perm:[1,0,3,2] row_mask:0xf bank_mask:0xf
	v_perm_b32 v200, v200, v162, v195
	ds_write_b32 v229, v200 offset:32
	s_nop 1
	v_mov_b32_dpp v228, v163 quad_perm:[1,0,3,2] row_mask:0xf bank_mask:0xf
	v_perm_b32 v228, v228, v163, v195
	ds_write_b32 v229, v228 offset:320
	ds_write_b64 v127, v[146:147] offset:9216
	ds_write_b64 v127, v[162:163] offset:11520
	v_cvt_pk_bf16_f32 v146, v60, v61
	s_nop 1
	v_mov_b32_dpp v200, v0 quad_perm:[1,0,3,2] row_mask:0xf bank_mask:0xf
	v_perm_b32 v200, v200, v0, v195
	ds_write_b32 v229, v200 offset:18432
	s_nop 1
	v_mov_b32_dpp v228, v146 quad_perm:[1,0,3,2] row_mask:0xf bank_mask:0xf
	v_perm_b32 v228, v228, v146, v195
	ds_write_b32 v229, v228 offset:18720
	v_cvt_pk_bf16_f32 v0, v62, v63
	v_cvt_pk_bf16_f32 v146, v64, v65
	s_nop 1
	v_mov_b32_dpp v200, v0 quad_perm:[1,0,3,2] row_mask:0xf bank_mask:0xf
	v_perm_b32 v200, v200, v0, v195
	ds_write_b32 v229, v200 offset:18464
	s_nop 1
	v_mov_b32_dpp v228, v146 quad_perm:[1,0,3,2] row_mask:0xf bank_mask:0xf
	v_perm_b32 v228, v228, v146, v195
	ds_write_b32 v229, v228 offset:18752
	s_waitcnt lgkmcnt(0)
	s_barrier
	ds_read_b128 v[186:189], v69 offset:18432
	ds_read_b128 v[190:193], v118 offset:9216
	ds_read_b128 v[204:207], v118 offset:11520
	ds_read_b128 v[208:211], v69 offset:18496
	ds_read_b128 v[212:215], v118 offset:9280
	ds_read_b128 v[216:219], v118 offset:11584
	s_nop 0
	s_nop 0
	s_waitcnt lgkmcnt(4)
	v_mfma_f32_16x16x32_bf16 v[58:61], v[186:189], v[190:193], v[58:61]
	s_nop 0
	s_waitcnt lgkmcnt(3)
	v_mfma_f32_16x16x32_bf16 v[62:65], v[186:189], v[204:207], v[62:65]
	s_nop 0
	s_nop 0
	s_waitcnt lgkmcnt(1)
	v_mfma_f32_16x16x32_bf16 v[58:61], v[208:211], v[212:215], v[58:61]
	s_nop 0
	s_waitcnt lgkmcnt(0)
	v_mfma_f32_16x16x32_bf16 v[62:65], v[208:211], v[216:219], v[62:65]
	v_mov_b32_e32 v162, v208
	v_mov_b32_e32 v163, v209
	v_mov_b32_e32 v164, v210
	v_mov_b32_e32 v165, v211
	v_mov_b32_e32 v166, v216
	v_mov_b32_e32 v167, v217
	v_mov_b32_e32 v168, v218
	v_mov_b32_e32 v169, v219
	s_nop 4
	v_cvt_pk_bf16_f32 v0, v58, v59
	v_cvt_pk_bf16_f32 v58, v60, v61
	s_nop 1
	v_mov_b32_dpp v200, v0 quad_perm:[1,0,3,2] row_mask:0xf bank_mask:0xf
	v_perm_b32 v200, v200, v0, v195
	ds_write_b32 v229, v200 offset:27648
	s_nop 1
	v_mov_b32_dpp v228, v58 quad_perm:[1,0,3,2] row_mask:0xf bank_mask:0xf
	v_perm_b32 v228, v228, v58, v195
	ds_write_b32 v229, v228 offset:27936
	v_cvt_pk_bf16_f32 v0, v62, v63
	v_cvt_pk_bf16_f32 v58, v64, v65
	s_nop 1
	v_mov_b32_dpp v200, v0 quad_perm:[1,0,3,2] row_mask:0xf bank_mask:0xf
	v_perm_b32 v200, v200, v0, v195
	ds_write_b32 v229, v200 offset:27680
	s_nop 1
	v_mov_b32_dpp v228, v58 quad_perm:[1,0,3,2] row_mask:0xf bank_mask:0xf
	v_perm_b32 v228, v228, v58, v195
	ds_write_b32 v229, v228 offset:27968
	v_mfma_f32_16x16x32_bf16 v[42:45], v[22:25], v[42:45], 0
	s_waitcnt lgkmcnt(0)
	s_barrier
	v_mfma_f32_16x16x32_bf16 v[58:61], v[22:25], v[46:49], 0
	v_mfma_f32_16x16x32_bf16 v[38:41], v[22:25], v[38:41], 0
	v_mfma_f32_16x16x32_bf16 v[34:37], v[22:25], v[34:37], 0
	v_mfma_f32_16x16x32_bf16 v[46:49], v[18:21], v[54:57], v[42:45]
	v_mfma_f32_16x16x32_bf16 v[42:45], v[18:21], v[50:53], v[58:61]
	v_mfma_f32_16x16x32_bf16 v[22:25], v[18:21], v[30:33], v[38:41]
	v_mfma_f32_16x16x32_bf16 v[18:21], v[18:21], v[26:29], v[34:37]
	s_and_saveexec_b64 s[12:13], vcc
	s_cbranch_execz .LBB0_245
	ds_read_b128 v[26:29], v68 offset:27648
	s_waitcnt lgkmcnt(0)
	global_store_dwordx4 v[100:101], v[26:29], off
